# layers 1-3: input RMS norm fused away (gate epilogue writes per-tile sums of squares of h2; in-proj reads h2 directly and scales its f32 accumulators per row before the bf16 store); rownorm phase and
# speedup vs baseline: 1.0021x; 1.0021x over previous
.LBB0_118:
	s_mov_b32 s2, s12
	v_writelane_b32 v255, s2, 30
	s_cmp_lg_u32 s12, 0
	s_mov_b64 s[38:39], -1
	v_writelane_b32 v255, s3, 31
	s_cselect_b64 s[2:3], -1, 0
	v_writelane_b32 v255, s2, 32
	s_and_b64 vcc, exec, s[2:3]
	s_nop 0
	v_writelane_b32 v255, s3, 33
	s_cbranch_vccz .LBB0_123
	s_branch .LBB0_182
	v_mov_b32_e32 v0, v177
	v_readlane_b32 s1, v255, 8
	v_mbcnt_lo_u32_b32 v0, -1, v0
	v_mbcnt_hi_u32_b32 v1, -1, v0
	v_add_u32_e32 v0, s85, v1
	v_ashrrev_i32_e32 v0, 6, v0
	v_add_u32_e32 v0, s1, v0
	s_movk_i32 s1, 0x4000
	v_cmp_gt_i32_e32 vcc, s1, v0
	s_and_saveexec_b64 s[38:39], vcc
	s_cbranch_execz .LBB0_122
	v_cmp_lt_i32_e32 vcc, v250, v197
	v_and_b32_e32 v4, 63, v1
	s_mov_b64 s[40:41], 0
	v_cndmask_b32_e32 v1, v193, v250, vcc
	v_cmp_lt_i32_e32 vcc, v199, v197
	v_lshlrev_b32_e32 v6, 2, v1
	s_nop 0
	v_cndmask_b32_e32 v1, v193, v199, vcc
	v_lshlrev_b32_e32 v7, 2, v1
	v_xor_b32_e32 v1, 8, v193
	v_cmp_lt_i32_e32 vcc, v1, v197
	s_nop 1
	v_cndmask_b32_e32 v1, v193, v1, vcc
	v_lshlrev_b32_e32 v8, 2, v1
	v_xor_b32_e32 v1, 4, v193
	v_cmp_lt_i32_e32 vcc, v1, v197
	s_nop 1
	v_cndmask_b32_e32 v1, v193, v1, vcc
	v_lshlrev_b32_e32 v9, 2, v1
	v_xor_b32_e32 v1, 2, v193
	v_cmp_lt_i32_e32 vcc, v1, v197
	s_nop 1
	v_cndmask_b32_e32 v1, v193, v1, vcc
	v_lshlrev_b32_e32 v10, 2, v1
	v_xor_b32_e32 v1, 1, v193
	v_cmp_lt_i32_e32 vcc, v1, v197
	s_nop 1
	v_cndmask_b32_e32 v1, v193, v1, vcc
	v_lshlrev_b32_e32 v11, 2, v1
	v_ashrrev_i32_e32 v1, 31, v0
	v_lshlrev_b64 v[2:3], 12, v[0:1]
	v_lshl_or_b32 v2, v4, 4, v2
	v_lshl_add_u64 v[2:3], s[62:63], 0, v[2:3]
	v_readfirstlane_b32 s1, v0
	s_mov_b32 s2, 0xdf13c000
	v_add_co_u32_e32 v232, vcc, s2, v2
	s_nop 1
	v_addc_co_u32_e32 v233, vcc, -1, v3, vcc
	global_load_dwordx4 v[200:203], v[2:3], off offset:0
	global_load_dwordx4 v[204:207], v[2:3], off offset:1024
	global_load_dwordx4 v[208:211], v[2:3], off offset:2048
	global_load_dwordx4 v[212:215], v[2:3], off offset:3072

.LBB0_182:
	s_or_b64 exec, exec, s[38:39]
	v_readlane_b32 s88, v255, 32
	s_and_b32 s88, s88, 0x20ec4000
	v_readlane_b32 s2, v255, 30
	v_readlane_b32 s3, v255, 31
	s_waitcnt lgkmcnt(0)
	v_mov_b32_e32 v0, v177
	s_barrier
	s_mov_b32 s3, s35
	v_writelane_b32 v255, s2, 30
	v_mbcnt_lo_u32_b32 v0, -1, v0
	v_mbcnt_hi_u32_b32 v0, -1, v0
	v_writelane_b32 v255, s3, 31
	v_readlane_b32 s2, v254, 17
	v_add_u32_e32 v5, s85, v0
	v_readlane_b32 s3, v254, 18
	s_andn2_b64 vcc, exec, s[2:3]
	v_readfirstlane_b32 s34, v5
	s_cbranch_vccnz .LBB0_194
	v_lshlrev_b32_e32 v4, 4, v5
	v_add_u32_e32 v2, 0x2000, v4
	v_ashrrev_i32_e32 v1, 31, v2
	v_lshrrev_b32_e32 v1, 22, v1
	v_add_u32_e32 v1, v2, v1
	v_ashrrev_i32_e32 v1, 10, v1
	v_mul_i32_i24_e32 v3, 0x400, v1
	v_sub_u32_e32 v2, v2, v3
	v_lshrrev_b32_e32 v3, 4, v2
	v_bitop3_b32 v3, v3, v2, 32 bitop3:0x6c
	v_ashrrev_i32_e32 v2, 31, v3
	v_lshrrev_b32_e32 v2, 26, v2
	v_add_u32_e32 v6, v3, v2
	v_lshlrev_b32_e32 v7, 3, v1
	v_readlane_b32 s2, v255, 30
	v_ashrrev_i32_e32 v2, 6, v6
	v_and_b32_e32 v7, -16, v7
	v_readlane_b32 s3, v255, 31
	v_add_u32_e32 v7, v2, v7
	v_and_b32_e32 v8, 3, v2
	s_mov_b32 s3, 0xfffe0
	v_lshrrev_b32_e32 v9, 2, v7
	v_lshlrev_b32_e32 v10, 1, v7
	v_and_b32_e32 v6, 0xc0, v6
	v_and_or_b32 v8, v7, s3, v8
	v_and_b32_e32 v9, 4, v9
	v_and_b32_e32 v10, 24, v10
	v_sub_u32_e32 v3, v3, v6
	v_mov_b32_e32 v12, 1
	v_or3_b32 v8, v8, v9, v10
	v_lshlrev_b32_e32 v9, 5, v1
	v_ashrrev_i16_sdwa v3, v12, sext(v3) dst_sel:DWORD dst_unused:UNUSED_PAD src0_sel:DWORD src1_sel:BYTE_0
	v_and_b32_e32 v9, 32, v9
	v_bfe_i32 v3, v3, 0, 16
	v_add_lshl_u32 v6, v9, v3, 1
	v_lshl_add_u32 v128, v8, 12, v6
	v_lshl_add_u32 v130, v7, 12, v6
	v_bfe_i32 v6, v5, 27, 1
	v_lshrrev_b32_e32 v6, 22, v6
	v_add_u32_e32 v6, v4, v6
	v_and_b32_e32 v6, 0xfffffc00, v6
	v_sub_u32_e32 v4, v4, v6
	v_lshrrev_b32_e32 v6, 4, v4
	v_ashrrev_i32_e32 v8, 31, v5
	v_bitop3_b32 v6, v6, v4, 32 bitop3:0x6c
	v_lshrrev_b32_e32 v8, 26, v8
	v_ashrrev_i32_e32 v4, 31, v6
	v_add_u32_e32 v5, v5, v8
	v_lshrrev_b32_e32 v4, 26, v4
	v_ashrrev_i32_e32 v5, 6, v5
	v_add_u32_e32 v7, v6, v4
	v_lshlrev_b32_e32 v8, 3, v5
	v_ashrrev_i32_e32 v4, 6, v7
	v_and_b32_e32 v8, -16, v8
	s_mul_hi_u32 s1, s2, 0x1b00000
	s_mul_i32 s2, s2, 0x1b00000
	v_readlane_b32 s12, v253, 2
	v_add_u32_e32 v8, v4, v8
	v_readlane_b32 s13, v253, 3
	s_add_u32 s49, s12, s2
	v_and_b32_e32 v9, 3, v4
	v_lshrrev_b32_e32 v10, 2, v8
	v_lshlrev_b32_e32 v11, 1, v8
	v_and_b32_e32 v7, 0xc0, v7
	s_addc_u32 s52, s13, s1
	s_ashr_i32 s2, s34, 6
	v_and_or_b32 v9, v8, s3, v9
	v_and_b32_e32 v10, 4, v10
	v_and_b32_e32 v11, 24, v11
	v_sub_u32_e32 v6, v6, v7
	s_ashr_i32 s1, s34, 8
	s_lshl_b32 s53, s2, 10
	v_or3_b32 v9, v9, v10, v11
	v_lshlrev_b32_e32 v10, 5, v5
	v_ashrrev_i16_sdwa v6, v12, sext(v6) dst_sel:DWORD dst_unused:UNUSED_PAD src0_sel:DWORD src1_sel:BYTE_0
	v_readlane_b32 s12, v254, 36
	v_and_b32_e32 v10, 32, v10
	v_bfe_i32 v6, v6, 0, 16
	v_readlane_b32 s13, v254, 37
	s_add_u32 s70, s49, s12
	v_add_lshl_u32 v7, v10, v6, 1
	s_addc_u32 s71, s52, s13
	s_add_i32 s60, s53, 0
	v_lshl_add_u32 v176, v9, 12, v7
	s_add_i32 m0, s60, 0x10000
	v_readlane_b32 s12, v254, 40
	global_load_lds_dwordx4 v176, s[70:71]
	s_add_i32 m0, s60, 0x12000
	v_lshl_add_u32 v132, v8, 12, v7
	global_load_lds_dwordx4 v128, s[70:71]
	s_mov_b32 m0, s60
	v_readlane_b32 s13, v254, 41
	s_add_u32 s12, s12, s88
	s_addc_u32 s13, s13, 0
	s_add_i32 s61, s60, 0x2000
	s_nop 3
	global_load_lds_dwordx4 v132, s[12:13]
	s_mov_b32 m0, s61
	s_nop 0
	global_load_lds_dwordx4 v130, s[12:13]
	s_add_u32 s12, s70, 0x80000
	s_addc_u32 s13, s71, 0
	s_add_i32 m0, s60, 0x14000
	s_add_i32 s74, s60, 0x4000
	global_load_lds_dwordx4 v176, s[12:13]
	s_add_i32 m0, s60, 0x16000
	s_add_i32 s75, s60, 0x6000
	global_load_lds_dwordx4 v128, s[12:13]
	v_readlane_b32 s12, v254, 42
	s_mov_b32 m0, s74
	v_readlane_b32 s13, v254, 43
	s_add_u32 s12, s12, s88
	s_addc_u32 s13, s13, 0
	s_cmp_lg_u32 s1, 1
	s_nop 3
	global_load_lds_dwordx4 v132, s[12:13]
	s_mov_b32 m0, s75
	s_nop 0
	global_load_lds_dwordx4 v130, s[12:13]
	s_cbranch_scc1 .LBB0_185
	s_barrier
.LBB0_185:
	v_lshl_add_u64 v[8:9], s[70:71], 0, v[176:177]
	v_mov_b32_e32 v129, v177
	v_readlane_b32 s68, v254, 40
	s_lshl_b32 s2, s2, 5
	v_lshl_add_u64 v[10:11], s[70:71], 0, v[128:129]
	v_mov_b32_e32 v133, v177
	v_readlane_b32 s69, v254, 41
	s_add_u32 s68, s68, s88
	s_addc_u32 s69, s69, 0
	s_and_b32 s13, s2, 0x60
	s_add_i32 m0, s60, 0x18000
	v_lshl_add_u64 v[8:9], v[8:9], 0, s[20:21]
	v_lshl_add_u64 v[12:13], s[68:69], 0, v[132:133]
	v_mov_b32_e32 v131, v177
	s_lshl_b32 s12, s1, 13
	s_lshl_b32 s14, s13, 7
	s_waitcnt vmcnt(4)
	s_barrier
	global_load_lds_dwordx4 v[8:9], off
	v_lshl_add_u64 v[8:9], v[10:11], 0, s[20:21]
	s_add_i32 m0, s60, 0x1a000
	s_add_i32 s76, s60, 0x8000
	s_add_i32 s77, s60, 0xa000
	v_lshl_add_u64 v[14:15], s[68:69], 0, v[130:131]
	global_load_lds_dwordx4 v[8:9], off
	v_lshl_add_u64 v[8:9], v[12:13], 0, s[20:21]
	s_mov_b32 m0, s76
	s_add_u32 s2, s70, 0x80080
	global_load_lds_dwordx4 v[8:9], off
	v_lshl_add_u64 v[8:9], v[14:15], 0, s[20:21]
	s_mov_b32 m0, s77
	s_addc_u32 s3, s71, 0
	global_load_lds_dwordx4 v[8:9], off
	s_add_i32 m0, s60, 0x1c000
	v_lshl_add_u64 v[8:9], s[2:3], 0, v[176:177]
	global_load_lds_dwordx4 v[8:9], off
	v_lshl_add_u64 v[8:9], s[2:3], 0, v[128:129]
	s_add_i32 m0, s60, 0x1e000
	v_and_b32_e32 v7, 15, v0
	global_load_lds_dwordx4 v[8:9], off
	v_lshrrev_b32_e32 v8, 1, v0
	v_and_b32_e32 v8, 24, v8
	v_lshlrev_b32_e32 v9, 1, v8
	v_lshlrev_b32_e32 v0, 2, v0
	v_lshl_or_b32 v142, s1, 6, v7
	v_lshl_or_b32 v7, v7, 6, v9
	v_and_b32_e32 v0, 32, v0
	v_bitop3_b32 v9, v7, s12, v0 bitop3:0xde
	v_bitop3_b32 v143, v7, s14, v0 bitop3:0xde
	v_lshlrev_b32_e32 v0, 15, v5
	v_and_b32_e32 v0, 0xffff0000, v0
	v_lshl_add_u32 v0, v4, 12, v0
	v_and_b32_e32 v4, 1, v5
	v_lshl_or_b32 v0, v4, 6, v0
	v_lshl_add_u32 v134, v6, 1, v0
	v_lshlrev_b32_e32 v0, 15, v1
	v_and_b32_e32 v0, 0xffff0000, v0
	s_waitcnt vmcnt(6)
	v_lshl_add_u32 v0, v2, 12, v0
	v_and_b32_e32 v1, 1, v1
	v_lshl_or_b32 v0, v1, 6, v0
	v_readlane_b32 s2, v254, 38
	v_or_b32_e32 v144, s13, v8
	v_mov_b32_e32 v135, v177
	v_lshl_add_u32 v136, v3, 1, v0
	v_mov_b32_e32 v137, v177
	s_mov_b32 s78, 0
	v_add_u32_e32 v145, 0, v9
	v_readlane_b32 s79, v254, 35
	s_mov_b32 s80, s2
	s_barrier
	v_readlane_b32 s3, v254, 39

.LBB0_188:
	s_ashr_i32 s43, s42, 31
	v_mov_b64_e32 v[0:1], 0x6c0
	s_lshl_b64 s[2:3], s[42:43], 20
	v_readlane_b32 s12, v255, 1
	v_cmp_lt_i64_e32 vcc, s[44:45], v[0:1]
	v_readlane_b32 s13, v255, 2
	s_add_u32 s44, s12, s2
	s_addc_u32 s45, s13, s3
	s_add_u32 s44, s44, s88
	s_addc_u32 s45, s45, 0
	s_and_b64 s[2:3], vcc, exec
	s_cselect_b32 s43, s45, s69
	s_cselect_b32 s81, s44, s68
	s_ashr_i32 s41, s40, 31
	s_lshl_b64 s[2:3], s[40:41], 20
	s_add_u32 s46, s49, s2
	s_addc_u32 s47, s52, s3
	s_and_b64 s[2:3], vcc, exec
	s_cselect_b32 s41, s47, s71
	s_cselect_b32 s82, s46, s70
	s_add_u32 s68, s68, 0x80080
	s_addc_u32 s69, s69, 0
	s_add_u32 s83, s70, 0x100
	v_mov_b32_e32 v0, 0
	s_addc_u32 s86, s71, 0
	s_mov_b32 s87, -2
	v_mov_b32_e32 v1, v0
	v_mov_b32_e32 v2, v0
	v_mov_b32_e32 v3, v0
	v_mov_b32_e32 v4, v0
	v_mov_b32_e32 v5, v0
	v_mov_b32_e32 v6, v0
	v_mov_b32_e32 v7, v0
	v_mov_b32_e32 v8, v0
	v_mov_b32_e32 v9, v0
	v_mov_b32_e32 v10, v0
	v_mov_b32_e32 v11, v0
	v_mov_b32_e32 v16, v0
	v_mov_b32_e32 v17, v0
	v_mov_b32_e32 v18, v0
	v_mov_b32_e32 v19, v0
	v_mov_b32_e32 v24, v0
	v_mov_b32_e32 v25, v0
	v_mov_b32_e32 v26, v0
	v_mov_b32_e32 v27, v0
	v_mov_b32_e32 v32, v0
	v_mov_b32_e32 v33, v0
	v_mov_b32_e32 v34, v0
	v_mov_b32_e32 v35, v0
	v_mov_b32_e32 v40, v0
	v_mov_b32_e32 v41, v0
	v_mov_b32_e32 v42, v0
	v_mov_b32_e32 v43, v0
	v_mov_b32_e32 v48, v0
	v_mov_b32_e32 v49, v0
	v_mov_b32_e32 v50, v0
	v_mov_b32_e32 v51, v0
	v_mov_b32_e32 v12, v0
	v_mov_b32_e32 v13, v0
	v_mov_b32_e32 v14, v0
	v_mov_b32_e32 v15, v0
	v_mov_b32_e32 v20, v0
	v_mov_b32_e32 v21, v0
	v_mov_b32_e32 v22, v0
	v_mov_b32_e32 v23, v0
	v_mov_b32_e32 v28, v0
	v_mov_b32_e32 v29, v0
	v_mov_b32_e32 v30, v0
	v_mov_b32_e32 v31, v0
	v_mov_b32_e32 v36, v0
	v_mov_b32_e32 v37, v0
	v_mov_b32_e32 v38, v0
	v_mov_b32_e32 v39, v0
	v_mov_b32_e32 v44, v0
	v_mov_b32_e32 v45, v0
	v_mov_b32_e32 v46, v0
	v_mov_b32_e32 v47, v0
	v_mov_b32_e32 v52, v0
	v_mov_b32_e32 v53, v0
	v_mov_b32_e32 v54, v0
	v_mov_b32_e32 v55, v0
	v_mov_b32_e32 v56, v0
	v_mov_b32_e32 v57, v0
	v_mov_b32_e32 v58, v0
	v_mov_b32_e32 v59, v0
	v_mov_b32_e32 v60, v0
	v_mov_b32_e32 v61, v0
	v_mov_b32_e32 v62, v0
	v_mov_b32_e32 v63, v0
	v_mov_b32_e32 v64, v0
	v_mov_b32_e32 v65, v0
	v_mov_b32_e32 v66, v0
	v_mov_b32_e32 v67, v0
	v_mov_b32_e32 v68, v0
	v_mov_b32_e32 v69, v0
	v_mov_b32_e32 v70, v0
	v_mov_b32_e32 v71, v0
	v_mov_b32_e32 v72, v0
	v_mov_b32_e32 v73, v0
	v_mov_b32_e32 v74, v0
	v_mov_b32_e32 v75, v0
	v_mov_b32_e32 v80, v0
	v_mov_b32_e32 v81, v0
	v_mov_b32_e32 v82, v0
	v_mov_b32_e32 v83, v0
	v_mov_b32_e32 v88, v0
	v_mov_b32_e32 v89, v0
	v_mov_b32_e32 v90, v0
	v_mov_b32_e32 v91, v0
	v_mov_b32_e32 v96, v0
	v_mov_b32_e32 v97, v0
	v_mov_b32_e32 v98, v0
	v_mov_b32_e32 v99, v0
	v_mov_b32_e32 v104, v0
	v_mov_b32_e32 v105, v0
	v_mov_b32_e32 v106, v0
	v_mov_b32_e32 v107, v0
	v_mov_b32_e32 v112, v0
	v_mov_b32_e32 v113, v0
	v_mov_b32_e32 v114, v0
	v_mov_b32_e32 v115, v0
	v_mov_b32_e32 v76, v0
	v_mov_b32_e32 v77, v0
	v_mov_b32_e32 v78, v0
	v_mov_b32_e32 v79, v0
	v_mov_b32_e32 v84, v0
	v_mov_b32_e32 v85, v0
	v_mov_b32_e32 v86, v0
	v_mov_b32_e32 v87, v0
	v_mov_b32_e32 v92, v0
	v_mov_b32_e32 v93, v0
	v_mov_b32_e32 v94, v0
	v_mov_b32_e32 v95, v0
	v_mov_b32_e32 v100, v0
	v_mov_b32_e32 v101, v0
	v_mov_b32_e32 v102, v0
	v_mov_b32_e32 v103, v0
	v_mov_b32_e32 v108, v0
	v_mov_b32_e32 v109, v0
	v_mov_b32_e32 v110, v0
	v_mov_b32_e32 v111, v0
	v_mov_b32_e32 v116, v0
	v_mov_b32_e32 v117, v0
	v_mov_b32_e32 v118, v0
	v_mov_b32_e32 v119, v0
	v_mov_b32_e32 v120, v0
	v_mov_b32_e32 v121, v0
	v_mov_b32_e32 v122, v0
	v_mov_b32_e32 v123, v0
	v_mov_b32_e32 v124, v0
	v_mov_b32_e32 v125, v0
	v_mov_b32_e32 v126, v0
	v_mov_b32_e32 v127, v0
.LBB0_189:
	s_add_u32 s1, s68, 0xfff80080
	s_addc_u32 s2, s69, -1
	s_add_i32 s3, 0, 0x10000
	v_add_u32_e32 v154, s3, v143
	ds_read_b128 v[138:141], v154
	ds_read_b128 v[146:149], v154 offset:1024
	ds_read_b128 v[150:153], v154 offset:2048
	ds_read_b128 v[154:157], v154 offset:3072
	s_cmp_eq_u32 s87, 28
	s_cselect_b32 s73, s43, s2
	s_cselect_b32 s72, s81, s1
	s_cselect_b32 s71, s41, s86
	s_cselect_b32 s70, s82, s83
	v_lshl_add_u64 v[174:175], s[68:69], 0, v[134:135]
	s_add_i32 m0, s60, 0xc000
	ds_read_b128 v[158:161], v145
	ds_read_b128 v[162:165], v145 offset:1024
	ds_read_b128 v[166:169], v145 offset:2048
	ds_read_b128 v[170:173], v145 offset:3072
	ds_read_b128 v[182:185], v145 offset:4096
	ds_read_b128 v[206:209], v145 offset:5120
	ds_read_b128 v[210:213], v145 offset:6144
	ds_read_b128 v[214:217], v145 offset:7168
	global_load_lds_dwordx4 v[174:175], off
	v_lshl_add_u64 v[174:175], s[68:69], 0, v[136:137]
	s_add_i32 m0, s60, 0xe000
	s_nop 0
	global_load_lds_dwordx4 v[174:175], off
	s_waitcnt lgkmcnt(8)
	s_barrier
	s_waitcnt lgkmcnt(0)
	s_setprio 1
	s_waitcnt lgkmcnt(0)
	v_mfma_f32_16x16x32_bf16 v[124:127], v[138:141], v[158:161], v[124:127]
	v_mfma_f32_16x16x32_bf16 v[120:123], v[150:153], v[158:161], v[120:123]
	v_mfma_f32_16x16x32_bf16 v[116:119], v[138:141], v[166:169], v[116:119]
	v_mfma_f32_16x16x32_bf16 v[108:111], v[150:153], v[166:169], v[108:111]
	v_mfma_f32_16x16x32_bf16 v[100:103], v[138:141], v[182:185], v[100:103]
	v_mfma_f32_16x16x32_bf16 v[92:95], v[150:153], v[182:185], v[92:95]
	v_mfma_f32_16x16x32_bf16 v[84:87], v[138:141], v[210:213], v[84:87]
	v_mfma_f32_16x16x32_bf16 v[76:79], v[150:153], v[210:213], v[76:79]
	v_mfma_f32_16x16x32_bf16 v[124:127], v[146:149], v[162:165], v[124:127]
	v_mfma_f32_16x16x32_bf16 v[120:123], v[154:157], v[162:165], v[120:123]
	v_mfma_f32_16x16x32_bf16 v[116:119], v[146:149], v[170:173], v[116:119]
	v_mfma_f32_16x16x32_bf16 v[108:111], v[154:157], v[170:173], v[108:111]
	v_mfma_f32_16x16x32_bf16 v[100:103], v[146:149], v[206:209], v[100:103]
	v_mfma_f32_16x16x32_bf16 v[92:95], v[154:157], v[206:209], v[92:95]
	v_mfma_f32_16x16x32_bf16 v[84:87], v[146:149], v[214:217], v[84:87]
	v_mfma_f32_16x16x32_bf16 v[76:79], v[154:157], v[214:217], v[76:79]
	s_setprio 0
	s_barrier
	s_add_i32 s1, 0, 0x14000
	v_add_u32_e32 v174, s1, v143
	s_add_i32 s2, s3, s53
	ds_read_b128 v[218:221], v174
	ds_read_b128 v[222:225], v174 offset:1024
	ds_read_b128 v[226:229], v174 offset:2048
	ds_read_b128 v[230:233], v174 offset:3072
	v_lshl_add_u64 v[174:175], s[70:71], 0, v[176:177]
	s_mov_b32 m0, s2
	v_lshl_add_u64 v[186:187], s[70:71], 0, v[128:129]
	global_load_lds_dwordx4 v[174:175], off
	s_add_i32 m0, s2, 0x2000
	s_nop 0
	global_load_lds_dwordx4 v[186:187], off
	s_barrier
	s_waitcnt lgkmcnt(0)
	s_setprio 1
	s_waitcnt lgkmcnt(0)
	v_mfma_f32_16x16x32_bf16 v[112:115], v[218:221], v[158:161], v[112:115]
	v_mfma_f32_16x16x32_bf16 v[104:107], v[226:229], v[158:161], v[104:107]
	v_mfma_f32_16x16x32_bf16 v[96:99], v[218:221], v[166:169], v[96:99]
	v_mfma_f32_16x16x32_bf16 v[88:91], v[226:229], v[166:169], v[88:91]
	v_mfma_f32_16x16x32_bf16 v[80:83], v[218:221], v[182:185], v[80:83]
	v_mfma_f32_16x16x32_bf16 v[72:75], v[226:229], v[182:185], v[72:75]
	v_mfma_f32_16x16x32_bf16 v[68:71], v[218:221], v[210:213], v[68:71]
	v_mfma_f32_16x16x32_bf16 v[64:67], v[226:229], v[210:213], v[64:67]
	v_mfma_f32_16x16x32_bf16 v[112:115], v[222:225], v[162:165], v[112:115]
	v_mfma_f32_16x16x32_bf16 v[104:107], v[230:233], v[162:165], v[104:107]
	v_mfma_f32_16x16x32_bf16 v[96:99], v[222:225], v[170:173], v[96:99]
	v_mfma_f32_16x16x32_bf16 v[88:91], v[230:233], v[170:173], v[88:91]
	v_mfma_f32_16x16x32_bf16 v[80:83], v[222:225], v[206:209], v[80:83]
	v_mfma_f32_16x16x32_bf16 v[72:75], v[230:233], v[206:209], v[72:75]
	v_mfma_f32_16x16x32_bf16 v[68:71], v[222:225], v[214:217], v[68:71]
	v_mfma_f32_16x16x32_bf16 v[64:67], v[230:233], v[214:217], v[64:67]
	s_setprio 0
	s_mov_b32 m0, s60
	v_lshl_add_u64 v[200:201], s[72:73], 0, v[132:133]
	s_barrier
	ds_read_b128 v[158:161], v145 offset:16384
	ds_read_b128 v[162:165], v145 offset:17408
	ds_read_b128 v[166:169], v145 offset:18432
	ds_read_b128 v[170:173], v145 offset:19456
	ds_read_b128 v[182:185], v145 offset:20480
	ds_read_b128 v[206:209], v145 offset:21504
	ds_read_b128 v[210:213], v145 offset:22528
	ds_read_b128 v[214:217], v145 offset:23552
	global_load_lds_dwordx4 v[200:201], off
	v_lshl_add_u64 v[202:203], s[72:73], 0, v[130:131]
	s_mov_b32 m0, s61
	s_nop 0
	global_load_lds_dwordx4 v[202:203], off
	s_barrier
	s_waitcnt lgkmcnt(0)
	s_setprio 1
	s_waitcnt lgkmcnt(0)
	v_mfma_f32_16x16x32_bf16 v[60:63], v[138:141], v[158:161], v[60:63]
	v_mfma_f32_16x16x32_bf16 v[56:59], v[150:153], v[158:161], v[56:59]
	v_mfma_f32_16x16x32_bf16 v[52:55], v[138:141], v[166:169], v[52:55]
	v_mfma_f32_16x16x32_bf16 v[44:47], v[150:153], v[166:169], v[44:47]
	v_mfma_f32_16x16x32_bf16 v[36:39], v[138:141], v[182:185], v[36:39]
	v_mfma_f32_16x16x32_bf16 v[28:31], v[150:153], v[182:185], v[28:31]
	v_mfma_f32_16x16x32_bf16 v[20:23], v[138:141], v[210:213], v[20:23]
	v_mfma_f32_16x16x32_bf16 v[12:15], v[150:153], v[210:213], v[12:15]
	v_mfma_f32_16x16x32_bf16 v[60:63], v[146:149], v[162:165], v[60:63]
	v_mfma_f32_16x16x32_bf16 v[56:59], v[154:157], v[162:165], v[56:59]
	v_mfma_f32_16x16x32_bf16 v[52:55], v[146:149], v[170:173], v[52:55]
	v_mfma_f32_16x16x32_bf16 v[44:47], v[154:157], v[170:173], v[44:47]
	v_mfma_f32_16x16x32_bf16 v[36:39], v[146:149], v[206:209], v[36:39]
	v_mfma_f32_16x16x32_bf16 v[28:31], v[154:157], v[206:209], v[28:31]
	v_mfma_f32_16x16x32_bf16 v[20:23], v[146:149], v[214:217], v[20:23]
	v_mfma_f32_16x16x32_bf16 v[12:15], v[154:157], v[214:217], v[12:15]
	s_setprio 0
	s_barrier
	s_add_u32 s2, s70, 0x80000
	s_addc_u32 s3, s71, 0
	s_add_i32 s1, s1, s53
	v_lshl_add_u64 v[138:139], s[2:3], 0, v[176:177]
	s_mov_b32 m0, s1
	s_nop 0
	global_load_lds_dwordx4 v[138:139], off
	v_lshl_add_u64 v[138:139], s[2:3], 0, v[128:129]
	s_add_i32 m0, s1, 0x2000
	s_nop 0
	global_load_lds_dwordx4 v[138:139], off
	s_waitcnt vmcnt(6)
	s_barrier
	s_setprio 1
	v_mfma_f32_16x16x32_bf16 v[48:51], v[218:221], v[158:161], v[48:51]
	v_mfma_f32_16x16x32_bf16 v[40:43], v[226:229], v[158:161], v[40:43]
	v_mfma_f32_16x16x32_bf16 v[32:35], v[218:221], v[166:169], v[32:35]
	v_mfma_f32_16x16x32_bf16 v[24:27], v[226:229], v[166:169], v[24:27]
	v_mfma_f32_16x16x32_bf16 v[16:19], v[218:221], v[182:185], v[16:19]
	v_mfma_f32_16x16x32_bf16 v[8:11], v[226:229], v[182:185], v[8:11]
	v_mfma_f32_16x16x32_bf16 v[4:7], v[218:221], v[210:213], v[4:7]
	v_mfma_f32_16x16x32_bf16 v[0:3], v[226:229], v[210:213], v[0:3]
	v_mfma_f32_16x16x32_bf16 v[48:51], v[222:225], v[162:165], v[48:51]
	v_mfma_f32_16x16x32_bf16 v[40:43], v[230:233], v[162:165], v[40:43]
	v_mfma_f32_16x16x32_bf16 v[32:35], v[222:225], v[170:173], v[32:35]
	v_mfma_f32_16x16x32_bf16 v[24:27], v[230:233], v[170:173], v[24:27]
	v_mfma_f32_16x16x32_bf16 v[16:19], v[222:225], v[206:209], v[16:19]
	v_mfma_f32_16x16x32_bf16 v[8:11], v[230:233], v[206:209], v[8:11]
	v_mfma_f32_16x16x32_bf16 v[4:7], v[222:225], v[214:217], v[4:7]
	v_mfma_f32_16x16x32_bf16 v[0:3], v[230:233], v[214:217], v[0:3]
	s_setprio 0
	s_add_i32 s1, 0, 0x18000
	v_add_u32_e32 v154, s1, v143
	s_barrier
	ds_read_b128 v[138:141], v154
	ds_read_b128 v[146:149], v154 offset:1024
	ds_read_b128 v[150:153], v154 offset:2048
	ds_read_b128 v[154:157], v154 offset:3072
	s_add_u32 s2, s72, 0x80000
	s_addc_u32 s3, s73, 0
	s_mov_b32 m0, s74
	v_lshl_add_u64 v[204:205], s[2:3], 0, v[132:133]
	ds_read_b128 v[158:161], v145 offset:32768
	ds_read_b128 v[162:165], v145 offset:33792
	ds_read_b128 v[166:169], v145 offset:34816
	ds_read_b128 v[170:173], v145 offset:35840
	ds_read_b128 v[182:185], v145 offset:36864
	ds_read_b128 v[206:209], v145 offset:37888
	ds_read_b128 v[210:213], v145 offset:38912
	ds_read_b128 v[214:217], v145 offset:39936
	global_load_lds_dwordx4 v[204:205], off
	v_lshl_add_u64 v[204:205], s[2:3], 0, v[130:131]
	s_mov_b32 m0, s75
	s_nop 0
	global_load_lds_dwordx4 v[204:205], off
	s_waitcnt lgkmcnt(8)
	s_barrier
	s_waitcnt lgkmcnt(0)
	s_setprio 1
	s_waitcnt lgkmcnt(0)
	v_mfma_f32_16x16x32_bf16 v[124:127], v[138:141], v[158:161], v[124:127]
	v_mfma_f32_16x16x32_bf16 v[120:123], v[150:153], v[158:161], v[120:123]
	v_mfma_f32_16x16x32_bf16 v[116:119], v[138:141], v[166:169], v[116:119]
	v_mfma_f32_16x16x32_bf16 v[108:111], v[150:153], v[166:169], v[108:111]
	v_mfma_f32_16x16x32_bf16 v[100:103], v[138:141], v[182:185], v[100:103]
	v_mfma_f32_16x16x32_bf16 v[92:95], v[150:153], v[182:185], v[92:95]
	v_mfma_f32_16x16x32_bf16 v[84:87], v[138:141], v[210:213], v[84:87]
	v_mfma_f32_16x16x32_bf16 v[76:79], v[150:153], v[210:213], v[76:79]
	v_mfma_f32_16x16x32_bf16 v[124:127], v[146:149], v[162:165], v[124:127]
	v_mfma_f32_16x16x32_bf16 v[120:123], v[154:157], v[162:165], v[120:123]
	v_mfma_f32_16x16x32_bf16 v[116:119], v[146:149], v[170:173], v[116:119]
	v_mfma_f32_16x16x32_bf16 v[108:111], v[154:157], v[170:173], v[108:111]
	v_mfma_f32_16x16x32_bf16 v[100:103], v[146:149], v[206:209], v[100:103]
	v_mfma_f32_16x16x32_bf16 v[92:95], v[154:157], v[206:209], v[92:95]
	v_mfma_f32_16x16x32_bf16 v[84:87], v[146:149], v[214:217], v[84:87]
	v_mfma_f32_16x16x32_bf16 v[76:79], v[154:157], v[214:217], v[76:79]
	s_setprio 0
	s_barrier
	s_add_i32 s12, 0, 0x1c000
	s_add_i32 s1, s1, s53
	v_add_u32_e32 v188, s12, v143
	v_lshl_add_u64 v[174:175], v[174:175], 0, s[20:21]
	s_mov_b32 m0, s1
	ds_read_b128 v[218:221], v188
	ds_read_b128 v[222:225], v188 offset:1024
	ds_read_b128 v[226:229], v188 offset:2048
	ds_read_b128 v[230:233], v188 offset:3072
	global_load_lds_dwordx4 v[174:175], off
	v_lshl_add_u64 v[174:175], v[186:187], 0, s[20:21]
	s_add_i32 m0, s1, 0x2000
	s_nop 0
	global_load_lds_dwordx4 v[174:175], off
	s_barrier
	s_waitcnt lgkmcnt(0)
	s_setprio 1
	s_waitcnt lgkmcnt(0)
	v_mfma_f32_16x16x32_bf16 v[112:115], v[218:221], v[158:161], v[112:115]
	v_mfma_f32_16x16x32_bf16 v[104:107], v[226:229], v[158:161], v[104:107]
	v_mfma_f32_16x16x32_bf16 v[96:99], v[218:221], v[166:169], v[96:99]
	v_mfma_f32_16x16x32_bf16 v[88:91], v[226:229], v[166:169], v[88:91]
	v_mfma_f32_16x16x32_bf16 v[80:83], v[218:221], v[182:185], v[80:83]
	v_mfma_f32_16x16x32_bf16 v[72:75], v[226:229], v[182:185], v[72:75]
	v_mfma_f32_16x16x32_bf16 v[68:71], v[218:221], v[210:213], v[68:71]
	v_mfma_f32_16x16x32_bf16 v[64:67], v[226:229], v[210:213], v[64:67]
	v_mfma_f32_16x16x32_bf16 v[112:115], v[222:225], v[162:165], v[112:115]
	v_mfma_f32_16x16x32_bf16 v[104:107], v[230:233], v[162:165], v[104:107]
	v_mfma_f32_16x16x32_bf16 v[96:99], v[222:225], v[170:173], v[96:99]
	v_mfma_f32_16x16x32_bf16 v[88:91], v[230:233], v[170:173], v[88:91]
	v_mfma_f32_16x16x32_bf16 v[80:83], v[222:225], v[206:209], v[80:83]
	v_mfma_f32_16x16x32_bf16 v[72:75], v[230:233], v[206:209], v[72:75]
	v_mfma_f32_16x16x32_bf16 v[68:71], v[222:225], v[214:217], v[68:71]
	v_mfma_f32_16x16x32_bf16 v[64:67], v[230:233], v[214:217], v[64:67]
	s_setprio 0
	s_mov_b32 m0, s76
	v_lshl_add_u64 v[174:175], v[200:201], 0, s[20:21]
	s_barrier
	ds_read_b128 v[158:161], v145 offset:49152
	ds_read_b128 v[162:165], v145 offset:50176
	ds_read_b128 v[166:169], v145 offset:51200
	ds_read_b128 v[170:173], v145 offset:52224
	ds_read_b128 v[182:185], v145 offset:53248
	ds_read_b128 v[206:209], v145 offset:54272
	ds_read_b128 v[210:213], v145 offset:55296
	ds_read_b128 v[214:217], v145 offset:56320
	global_load_lds_dwordx4 v[174:175], off
	v_lshl_add_u64 v[174:175], v[202:203], 0, s[20:21]
	s_mov_b32 m0, s77
	s_nop 0
	global_load_lds_dwordx4 v[174:175], off
	s_barrier
	s_waitcnt lgkmcnt(0)
	s_setprio 1
	s_waitcnt lgkmcnt(0)
	v_mfma_f32_16x16x32_bf16 v[60:63], v[138:141], v[158:161], v[60:63]
	v_mfma_f32_16x16x32_bf16 v[56:59], v[150:153], v[158:161], v[56:59]
	v_mfma_f32_16x16x32_bf16 v[52:55], v[138:141], v[166:169], v[52:55]
	v_mfma_f32_16x16x32_bf16 v[44:47], v[150:153], v[166:169], v[44:47]
	v_mfma_f32_16x16x32_bf16 v[36:39], v[138:141], v[182:185], v[36:39]
	v_mfma_f32_16x16x32_bf16 v[28:31], v[150:153], v[182:185], v[28:31]
	v_mfma_f32_16x16x32_bf16 v[20:23], v[138:141], v[210:213], v[20:23]
	v_mfma_f32_16x16x32_bf16 v[12:15], v[150:153], v[210:213], v[12:15]
	v_mfma_f32_16x16x32_bf16 v[60:63], v[146:149], v[162:165], v[60:63]
	v_mfma_f32_16x16x32_bf16 v[56:59], v[154:157], v[162:165], v[56:59]
	v_mfma_f32_16x16x32_bf16 v[52:55], v[146:149], v[170:173], v[52:55]
	v_mfma_f32_16x16x32_bf16 v[44:47], v[154:157], v[170:173], v[44:47]
	v_mfma_f32_16x16x32_bf16 v[36:39], v[146:149], v[206:209], v[36:39]
	v_mfma_f32_16x16x32_bf16 v[28:31], v[154:157], v[206:209], v[28:31]
	v_mfma_f32_16x16x32_bf16 v[20:23], v[146:149], v[214:217], v[20:23]
	v_mfma_f32_16x16x32_bf16 v[12:15], v[154:157], v[214:217], v[12:15]
	s_setprio 0
	s_barrier
	s_add_u32 s2, s70, 0x80080
	s_addc_u32 s3, s71, 0
	s_add_i32 s1, s12, s53
	v_lshl_add_u64 v[138:139], s[2:3], 0, v[176:177]
	s_mov_b32 m0, s1
	s_nop 0
	global_load_lds_dwordx4 v[138:139], off
	v_lshl_add_u64 v[138:139], s[2:3], 0, v[128:129]
	s_add_i32 m0, s1, 0x2000
	s_nop 0
	global_load_lds_dwordx4 v[138:139], off
	s_waitcnt vmcnt(6)
	s_barrier
	s_setprio 1
	v_mfma_f32_16x16x32_bf16 v[48:51], v[218:221], v[158:161], v[48:51]
	v_mfma_f32_16x16x32_bf16 v[40:43], v[226:229], v[158:161], v[40:43]
	v_mfma_f32_16x16x32_bf16 v[32:35], v[218:221], v[166:169], v[32:35]
	v_mfma_f32_16x16x32_bf16 v[24:27], v[226:229], v[166:169], v[24:27]
	v_mfma_f32_16x16x32_bf16 v[16:19], v[218:221], v[182:185], v[16:19]
	v_mfma_f32_16x16x32_bf16 v[8:11], v[226:229], v[182:185], v[8:11]
	v_mfma_f32_16x16x32_bf16 v[4:7], v[218:221], v[210:213], v[4:7]
	v_mfma_f32_16x16x32_bf16 v[0:3], v[226:229], v[210:213], v[0:3]
	v_mfma_f32_16x16x32_bf16 v[48:51], v[222:225], v[162:165], v[48:51]
	v_mfma_f32_16x16x32_bf16 v[40:43], v[230:233], v[162:165], v[40:43]
	v_mfma_f32_16x16x32_bf16 v[32:35], v[222:225], v[170:173], v[32:35]
	v_mfma_f32_16x16x32_bf16 v[24:27], v[230:233], v[170:173], v[24:27]
	v_mfma_f32_16x16x32_bf16 v[16:19], v[222:225], v[206:209], v[16:19]
	v_mfma_f32_16x16x32_bf16 v[8:11], v[230:233], v[206:209], v[8:11]
	v_mfma_f32_16x16x32_bf16 v[4:7], v[222:225], v[214:217], v[4:7]
	v_mfma_f32_16x16x32_bf16 v[0:3], v[230:233], v[214:217], v[0:3]
	s_setprio 0
	s_add_i32 s87, s87, 2
	s_add_u32 s68, s68, 0x100
	s_addc_u32 s69, s69, 0
	s_add_u32 s83, s83, 0x100
	s_addc_u32 s86, s86, 0
	s_cmp_gt_u32 s87, 29
	s_barrier
	s_cbranch_scc0 .LBB0_189
	s_cmp_eq_u32 s88, 0
	s_cbranch_scc1 .Lrs_skip
	v_readlane_b32 s98, v255, 1
	v_readlane_b32 s99, v255, 2
	v_lshl_add_u32 v200, s80, 8, v142
	v_bfe_u32 v201, v144, 3, 2
	v_lshlrev_b32_e32 v201, 5, v201
	v_lshl_add_u32 v200, v200, 7, v201
	v_add_u32_e32 v201, 0x1000, v200
	v_add_u32_e32 v202, 0x4000, v200
	v_add_u32_e32 v203, 0x5000, v200
	v_mbcnt_lo_u32_b32 v204, -1, 0
	v_mbcnt_hi_u32_b32 v204, -1, v204
	v_xor_b32_e32 v205, 16, v204
	v_xor_b32_e32 v204, 32, v204
	v_lshlrev_b32_e32 v205, 2, v205
	v_lshlrev_b32_e32 v204, 2, v204
	global_load_dwordx4 v[208:211], v200, s[98:99]
	global_load_dwordx4 v[212:215], v200, s[98:99] offset:16
	global_load_dwordx4 v[216:219], v200, s[98:99] offset:2048
	global_load_dwordx4 v[220:223], v200, s[98:99] offset:2064
	global_load_dwordx4 v[224:227], v201, s[98:99]
	global_load_dwordx4 v[228:231], v201, s[98:99] offset:16
	global_load_dwordx4 v[232:235], v201, s[98:99] offset:2048
	global_load_dwordx4 v[236:239], v201, s[98:99] offset:2064
	s_waitcnt vmcnt(0)
	v_add_f32_e32 v208, v208, v209
	v_add_f32_e32 v210, v210, v211
	v_add_f32_e32 v212, v212, v213
	v_add_f32_e32 v214, v214, v215
	v_add_f32_e32 v208, v208, v210
	v_add_f32_e32 v212, v212, v214
	v_add_f32_e32 v240, v208, v212
	v_add_f32_e32 v216, v216, v217
	v_add_f32_e32 v218, v218, v219
	v_add_f32_e32 v220, v220, v221
	v_add_f32_e32 v222, v222, v223
	v_add_f32_e32 v216, v216, v218
	v_add_f32_e32 v220, v220, v222
	v_add_f32_e32 v241, v216, v220
	v_add_f32_e32 v224, v224, v225
	v_add_f32_e32 v226, v226, v227
	v_add_f32_e32 v228, v228, v229
	v_add_f32_e32 v230, v230, v231
	v_add_f32_e32 v224, v224, v226
	v_add_f32_e32 v228, v228, v230
	v_add_f32_e32 v242, v224, v228
	v_add_f32_e32 v232, v232, v233
	v_add_f32_e32 v234, v234, v235
	v_add_f32_e32 v236, v236, v237
	v_add_f32_e32 v238, v238, v239
	v_add_f32_e32 v232, v232, v234
	v_add_f32_e32 v236, v236, v238
	v_add_f32_e32 v243, v232, v236
	global_load_dwordx4 v[208:211], v202, s[98:99]
	global_load_dwordx4 v[212:215], v202, s[98:99] offset:16
	global_load_dwordx4 v[216:219], v202, s[98:99] offset:2048
	global_load_dwordx4 v[220:223], v202, s[98:99] offset:2064
	global_load_dwordx4 v[224:227], v203, s[98:99]
	global_load_dwordx4 v[228:231], v203, s[98:99] offset:16
	global_load_dwordx4 v[232:235], v203, s[98:99] offset:2048
	global_load_dwordx4 v[236:239], v203, s[98:99] offset:2064
	s_waitcnt vmcnt(0)
	v_add_f32_e32 v208, v208, v209
	v_add_f32_e32 v210, v210, v211
	v_add_f32_e32 v212, v212, v213
	v_add_f32_e32 v214, v214, v215
	v_add_f32_e32 v208, v208, v210
	v_add_f32_e32 v212, v212, v214
	v_add_f32_e32 v244, v208, v212
	v_add_f32_e32 v216, v216, v217
	v_add_f32_e32 v218, v218, v219
	v_add_f32_e32 v220, v220, v221
	v_add_f32_e32 v222, v222, v223
	v_add_f32_e32 v216, v216, v218
	v_add_f32_e32 v220, v220, v222
	v_add_f32_e32 v245, v216, v220
	v_add_f32_e32 v224, v224, v225
	v_add_f32_e32 v226, v226, v227
	v_add_f32_e32 v228, v228, v229
	v_add_f32_e32 v230, v230, v231
	v_add_f32_e32 v224, v224, v226
	v_add_f32_e32 v228, v228, v230
	v_add_f32_e32 v246, v224, v228
	v_add_f32_e32 v232, v232, v233
	v_add_f32_e32 v234, v234, v235
	v_add_f32_e32 v236, v236, v237
	v_add_f32_e32 v238, v238, v239
	v_add_f32_e32 v232, v232, v234
	v_add_f32_e32 v236, v236, v238
	v_add_f32_e32 v247, v232, v236
	ds_bpermute_b32 v208, v205, v240
	ds_bpermute_b32 v209, v205, v241
	ds_bpermute_b32 v210, v205, v242
	ds_bpermute_b32 v211, v205, v243
	ds_bpermute_b32 v212, v205, v244
	ds_bpermute_b32 v213, v205, v245
	ds_bpermute_b32 v214, v205, v246
	ds_bpermute_b32 v215, v205, v247
	s_waitcnt lgkmcnt(0)
	v_add_f32_e32 v240, v240, v208
	v_add_f32_e32 v241, v241, v209
	v_add_f32_e32 v242, v242, v210
	v_add_f32_e32 v243, v243, v211
	v_add_f32_e32 v244, v244, v212
	v_add_f32_e32 v245, v245, v213
	v_add_f32_e32 v246, v246, v214
	v_add_f32_e32 v247, v247, v215
	ds_bpermute_b32 v208, v204, v240
	ds_bpermute_b32 v209, v204, v241
	ds_bpermute_b32 v210, v204, v242
	ds_bpermute_b32 v211, v204, v243
	ds_bpermute_b32 v212, v204, v244
	ds_bpermute_b32 v213, v204, v245
	ds_bpermute_b32 v214, v204, v246
	ds_bpermute_b32 v215, v204, v247
	s_waitcnt lgkmcnt(0)
	v_add_f32_e32 v240, v240, v208
	v_add_f32_e32 v241, v241, v209
	v_add_f32_e32 v242, v242, v210
	v_add_f32_e32 v243, v243, v211
	v_add_f32_e32 v244, v244, v212
	v_add_f32_e32 v245, v245, v213
	v_add_f32_e32 v246, v246, v214
	v_add_f32_e32 v247, v247, v215
	v_mul_f32_e32 v240, 0x3a000000, v240
	v_add_f32_e32 v240, 0x358637bd, v240
	v_mul_f32_e32 v241, 0x3a000000, v241
	v_add_f32_e32 v241, 0x358637bd, v241
	v_mul_f32_e32 v242, 0x3a000000, v242
	v_add_f32_e32 v242, 0x358637bd, v242
	v_mul_f32_e32 v243, 0x3a000000, v243
	v_add_f32_e32 v243, 0x358637bd, v243
	v_mul_f32_e32 v244, 0x3a000000, v244
	v_add_f32_e32 v244, 0x358637bd, v244
	v_mul_f32_e32 v245, 0x3a000000, v245
	v_add_f32_e32 v245, 0x358637bd, v245
	v_mul_f32_e32 v246, 0x3a000000, v246
	v_add_f32_e32 v246, 0x358637bd, v246
	v_mul_f32_e32 v247, 0x3a000000, v247
	v_add_f32_e32 v247, 0x358637bd, v247
	v_rsq_f32_e32 v240, v240
	v_rsq_f32_e32 v241, v241
	v_rsq_f32_e32 v242, v242
	v_rsq_f32_e32 v243, v243
	v_rsq_f32_e32 v244, v244
	v_rsq_f32_e32 v245, v245
	v_rsq_f32_e32 v246, v246
	v_rsq_f32_e32 v247, v247
	s_nop 0
	v_mul_f32_e32 v124, v124, v240
	v_mul_f32_e32 v125, v125, v240
	v_mul_f32_e32 v126, v126, v240
	v_mul_f32_e32 v127, v127, v240
	v_mul_f32_e32 v120, v120, v240
	v_mul_f32_e32 v121, v121, v240
	v_mul_f32_e32 v122, v122, v240
	v_mul_f32_e32 v123, v123, v240
	v_mul_f32_e32 v112, v112, v240
	v_mul_f32_e32 v113, v113, v240
	v_mul_f32_e32 v114, v114, v240
	v_mul_f32_e32 v115, v115, v240
	v_mul_f32_e32 v104, v104, v240
	v_mul_f32_e32 v105, v105, v240
	v_mul_f32_e32 v106, v106, v240
	v_mul_f32_e32 v107, v107, v240
	v_mul_f32_e32 v116, v116, v241
	v_mul_f32_e32 v117, v117, v241
	v_mul_f32_e32 v118, v118, v241
	v_mul_f32_e32 v119, v119, v241
	v_mul_f32_e32 v108, v108, v241
	v_mul_f32_e32 v109, v109, v241
	v_mul_f32_e32 v110, v110, v241
	v_mul_f32_e32 v111, v111, v241
	v_mul_f32_e32 v96, v96, v241
	v_mul_f32_e32 v97, v97, v241
	v_mul_f32_e32 v98, v98, v241
	v_mul_f32_e32 v99, v99, v241
	v_mul_f32_e32 v88, v88, v241
	v_mul_f32_e32 v89, v89, v241
	v_mul_f32_e32 v90, v90, v241
	v_mul_f32_e32 v91, v91, v241
	v_mul_f32_e32 v100, v100, v242
	v_mul_f32_e32 v101, v101, v242
	v_mul_f32_e32 v102, v102, v242
	v_mul_f32_e32 v103, v103, v242
	v_mul_f32_e32 v92, v92, v242
	v_mul_f32_e32 v93, v93, v242
	v_mul_f32_e32 v94, v94, v242
	v_mul_f32_e32 v95, v95, v242
	v_mul_f32_e32 v80, v80, v242
	v_mul_f32_e32 v81, v81, v242
	v_mul_f32_e32 v82, v82, v242
	v_mul_f32_e32 v83, v83, v242
	v_mul_f32_e32 v72, v72, v242
	v_mul_f32_e32 v73, v73, v242
	v_mul_f32_e32 v74, v74, v242
	v_mul_f32_e32 v75, v75, v242
	v_mul_f32_e32 v84, v84, v243
	v_mul_f32_e32 v85, v85, v243
	v_mul_f32_e32 v86, v86, v243
	v_mul_f32_e32 v87, v87, v243
	v_mul_f32_e32 v76, v76, v243
	v_mul_f32_e32 v77, v77, v243
	v_mul_f32_e32 v78, v78, v243
	v_mul_f32_e32 v79, v79, v243
	v_mul_f32_e32 v68, v68, v243
	v_mul_f32_e32 v69, v69, v243
	v_mul_f32_e32 v70, v70, v243
	v_mul_f32_e32 v71, v71, v243
	v_mul_f32_e32 v64, v64, v243
	v_mul_f32_e32 v65, v65, v243
	v_mul_f32_e32 v66, v66, v243
	v_mul_f32_e32 v67, v67, v243
	v_mul_f32_e32 v60, v60, v244
	v_mul_f32_e32 v61, v61, v244
	v_mul_f32_e32 v62, v62, v244
	v_mul_f32_e32 v63, v63, v244
	v_mul_f32_e32 v56, v56, v244
	v_mul_f32_e32 v57, v57, v244
	v_mul_f32_e32 v58, v58, v244
	v_mul_f32_e32 v59, v59, v244
	v_mul_f32_e32 v48, v48, v244
	v_mul_f32_e32 v49, v49, v244
	v_mul_f32_e32 v50, v50, v244
	v_mul_f32_e32 v51, v51, v244
	v_mul_f32_e32 v40, v40, v244
	v_mul_f32_e32 v41, v41, v244
	v_mul_f32_e32 v42, v42, v244
	v_mul_f32_e32 v43, v43, v244
	v_mul_f32_e32 v52, v52, v245
	v_mul_f32_e32 v53, v53, v245
	v_mul_f32_e32 v54, v54, v245
	v_mul_f32_e32 v55, v55, v245
	v_mul_f32_e32 v44, v44, v245
	v_mul_f32_e32 v45, v45, v245
	v_mul_f32_e32 v46, v46, v245
	v_mul_f32_e32 v47, v47, v245
	v_mul_f32_e32 v32, v32, v245
	v_mul_f32_e32 v33, v33, v245
	v_mul_f32_e32 v34, v34, v245
	v_mul_f32_e32 v35, v35, v245
	v_mul_f32_e32 v24, v24, v245
	v_mul_f32_e32 v25, v25, v245
	v_mul_f32_e32 v26, v26, v245
	v_mul_f32_e32 v27, v27, v245
	v_mul_f32_e32 v36, v36, v246
	v_mul_f32_e32 v37, v37, v246
	v_mul_f32_e32 v38, v38, v246
	v_mul_f32_e32 v39, v39, v246
	v_mul_f32_e32 v28, v28, v246
	v_mul_f32_e32 v29, v29, v246
	v_mul_f32_e32 v30, v30, v246
	v_mul_f32_e32 v31, v31, v246
	v_mul_f32_e32 v16, v16, v246
	v_mul_f32_e32 v17, v17, v246
	v_mul_f32_e32 v18, v18, v246
	v_mul_f32_e32 v19, v19, v246
	v_mul_f32_e32 v8, v8, v246
	v_mul_f32_e32 v9, v9, v246
	v_mul_f32_e32 v10, v10, v246
	v_mul_f32_e32 v11, v11, v246
	v_mul_f32_e32 v20, v20, v247
	v_mul_f32_e32 v21, v21, v247
	v_mul_f32_e32 v22, v22, v247
	v_mul_f32_e32 v23, v23, v247
	v_mul_f32_e32 v12, v12, v247
	v_mul_f32_e32 v13, v13, v247
	v_mul_f32_e32 v14, v14, v247
	v_mul_f32_e32 v15, v15, v247
	v_mul_f32_e32 v4, v4, v247
	v_mul_f32_e32 v5, v5, v247
	v_mul_f32_e32 v6, v6, v247
	v_mul_f32_e32 v7, v7, v247
	v_mul_f32_e32 v0, v0, v247
	v_mul_f32_e32 v1, v1, v247
	v_mul_f32_e32 v2, v2, v247
	v_mul_f32_e32 v3, v3, v247
.Lrs_skip:
	v_readlane_b32 s2, v253, 5
	v_lshl_or_b32 v140, s79, 8, v144
	v_readlane_b32 s3, v253, 6
	v_lshl_add_u32 v148, s80, 8, v142
	v_ashrrev_i32_e32 v141, 31, v140
	v_mov_b64_e32 v[138:139], s[2:3]
	v_mad_i64_i32 v[146:147], s[2:3], v148, s84, v[138:139]
	v_lshlrev_b64 v[140:141], 1, v[140:141]
	v_lshl_add_u64 v[146:147], v[146:147], 0, v[140:141]
	v_cvt_pk_bf16_f32 v124, v124, v125
	v_cvt_pk_bf16_f32 v125, v126, v127
	v_cvt_pk_bf16_f32 v126, v120, v121
	v_cvt_pk_bf16_f32 v127, v122, v123
	global_store_dwordx4 v[146:147], v[124:127], off
	v_cvt_pk_bf16_f32 v112, v112, v113
	v_cvt_pk_bf16_f32 v113, v114, v115
	v_cvt_pk_bf16_f32 v114, v104, v105
	v_or_b32_e32 v104, 16, v148
	v_mad_i64_i32 v[104:105], s[2:3], v104, s84, v[138:139]
	v_cvt_pk_bf16_f32 v115, v106, v107
	global_store_dwordx4 v[146:147], v[112:115], off offset:256
	s_and_b64 vcc, exec, s[38:39]
	s_mov_b32 s79, s40
	v_lshl_add_u64 v[112:113], v[104:105], 0, v[140:141]
	v_cvt_pk_bf16_f32 v104, v116, v117
	v_cvt_pk_bf16_f32 v105, v118, v119
	v_cvt_pk_bf16_f32 v106, v108, v109
	v_cvt_pk_bf16_f32 v107, v110, v111
	global_store_dwordx4 v[112:113], v[104:107], off
	v_cvt_pk_bf16_f32 v96, v96, v97
	v_cvt_pk_bf16_f32 v97, v98, v99
	v_cvt_pk_bf16_f32 v98, v88, v89
	v_or_b32_e32 v88, 32, v148
	v_mad_i64_i32 v[88:89], s[2:3], v88, s84, v[138:139]
	v_cvt_pk_bf16_f32 v99, v90, v91
	global_store_dwordx4 v[112:113], v[96:99], off offset:256
	s_mov_b32 s80, s42
	s_mov_b64 s[70:71], s[46:47]
	v_lshl_add_u64 v[96:97], v[88:89], 0, v[140:141]
	v_cvt_pk_bf16_f32 v88, v100, v101
	v_cvt_pk_bf16_f32 v89, v102, v103
	v_cvt_pk_bf16_f32 v90, v92, v93
	v_cvt_pk_bf16_f32 v91, v94, v95
	global_store_dwordx4 v[96:97], v[88:91], off
	v_cvt_pk_bf16_f32 v80, v80, v81
	v_cvt_pk_bf16_f32 v81, v82, v83
	v_cvt_pk_bf16_f32 v82, v72, v73
	v_or_b32_e32 v72, 48, v148
	v_mad_i64_i32 v[72:73], s[2:3], v72, s84, v[138:139]
	v_cvt_pk_bf16_f32 v83, v74, v75
	global_store_dwordx4 v[96:97], v[80:83], off offset:256
	s_mov_b64 s[68:69], s[44:45]
	s_nop 0
	v_lshl_add_u64 v[80:81], v[72:73], 0, v[140:141]
	v_cvt_pk_bf16_f32 v72, v84, v85
	v_cvt_pk_bf16_f32 v73, v86, v87
	v_cvt_pk_bf16_f32 v74, v76, v77
	v_cvt_pk_bf16_f32 v75, v78, v79
	global_store_dwordx4 v[80:81], v[72:75], off
	v_cvt_pk_bf16_f32 v68, v68, v69
	v_cvt_pk_bf16_f32 v69, v70, v71
	v_cvt_pk_bf16_f32 v70, v64, v65
	v_add_u32_e32 v64, 0x80, v148
	v_mad_i64_i32 v[64:65], s[2:3], v64, s84, v[138:139]
	v_lshl_add_u64 v[64:65], v[64:65], 0, v[140:141]
	v_cvt_pk_bf16_f32 v71, v66, v67
	global_store_dwordx4 v[80:81], v[68:71], off offset:256
	v_cvt_pk_bf16_f32 v60, v60, v61
	v_cvt_pk_bf16_f32 v61, v62, v63
	v_cvt_pk_bf16_f32 v62, v56, v57
	v_cvt_pk_bf16_f32 v63, v58, v59
	global_store_dwordx4 v[64:65], v[60:63], off
	v_cvt_pk_bf16_f32 v48, v48, v49
	v_cvt_pk_bf16_f32 v49, v50, v51
	v_cvt_pk_bf16_f32 v50, v40, v41
	v_add_u32_e32 v40, 0x90, v148
	v_mad_i64_i32 v[40:41], s[2:3], v40, s84, v[138:139]
	v_cvt_pk_bf16_f32 v51, v42, v43
	global_store_dwordx4 v[64:65], v[48:51], off offset:256
	s_nop 1
	v_lshl_add_u64 v[48:49], v[40:41], 0, v[140:141]
	v_cvt_pk_bf16_f32 v40, v52, v53
	v_cvt_pk_bf16_f32 v41, v54, v55
	v_cvt_pk_bf16_f32 v42, v44, v45
	v_cvt_pk_bf16_f32 v43, v46, v47
	global_store_dwordx4 v[48:49], v[40:43], off
	v_cvt_pk_bf16_f32 v32, v32, v33
	v_cvt_pk_bf16_f32 v33, v34, v35
	v_cvt_pk_bf16_f32 v34, v24, v25
	v_add_u32_e32 v24, 0xa0, v148
	v_mad_i64_i32 v[24:25], s[2:3], v24, s84, v[138:139]
	v_cvt_pk_bf16_f32 v35, v26, v27
	global_store_dwordx4 v[48:49], v[32:35], off offset:256
	s_nop 1
	v_lshl_add_u64 v[32:33], v[24:25], 0, v[140:141]
	v_cvt_pk_bf16_f32 v24, v36, v37
	v_cvt_pk_bf16_f32 v25, v38, v39
	v_cvt_pk_bf16_f32 v26, v28, v29
	v_cvt_pk_bf16_f32 v27, v30, v31
	global_store_dwordx4 v[32:33], v[24:27], off
	v_cvt_pk_bf16_f32 v16, v16, v17
	v_cvt_pk_bf16_f32 v17, v18, v19
	v_cvt_pk_bf16_f32 v18, v8, v9
	v_add_u32_e32 v8, 0xb0, v148
	v_mad_i64_i32 v[8:9], s[2:3], v8, s84, v[138:139]
	v_cvt_pk_bf16_f32 v19, v10, v11
	global_store_dwordx4 v[32:33], v[16:19], off offset:256
	s_nop 1
	v_lshl_add_u64 v[16:17], v[8:9], 0, v[140:141]
	v_cvt_pk_bf16_f32 v8, v20, v21
	v_cvt_pk_bf16_f32 v9, v22, v23
	v_cvt_pk_bf16_f32 v10, v12, v13
	v_cvt_pk_bf16_f32 v11, v14, v15
	global_store_dwordx4 v[16:17], v[8:11], off
	v_cvt_pk_bf16_f32 v4, v4, v5
	v_cvt_pk_bf16_f32 v5, v6, v7
	v_cvt_pk_bf16_f32 v6, v0, v1
	v_cvt_pk_bf16_f32 v7, v2, v3
	global_store_dwordx4 v[16:17], v[4:7], off offset:256
	s_cbranch_vccz .LBB0_186
	s_waitcnt vmcnt(0)
	s_cmpk_gt_u32 s34, 0xff
	s_cbranch_scc1 .LBB0_193
	s_barrier

.LBB0_647:
	s_add_u32 s1, s42, 0xfff80080
	s_addc_u32 s2, s43, -1
	s_add_i32 s3, 0, 0x10000
	v_add_u32_e32 v138, s3, v141
	ds_read_b128 v[134:137], v138
	ds_read_b128 v[142:145], v138 offset:1024
	ds_read_b128 v[150:153], v138 offset:2048
	ds_read_b128 v[154:157], v138 offset:3072
	s_cmp_eq_u32 s88, 28
	s_cselect_b32 s73, s45, s2
	s_cselect_b32 s72, s53, s1
	s_cselect_b32 s71, s47, s87
	s_cselect_b32 s70, s60, s61
	v_lshl_add_u64 v[138:139], s[42:43], 0, v[130:131]
	s_add_i32 m0, s77, 0xc000
	ds_read_b128 v[158:161], v149
	ds_read_b128 v[162:165], v149 offset:1024
	ds_read_b128 v[166:169], v149 offset:2048
	ds_read_b128 v[170:173], v149 offset:3072
	ds_read_b128 v[182:185], v149 offset:4096
	ds_read_b128 v[200:203], v149 offset:5120
	ds_read_b128 v[208:211], v149 offset:6144
	ds_read_b128 v[212:215], v149 offset:7168
	global_load_lds_dwordx4 v[138:139], off
	v_lshl_add_u64 v[138:139], s[42:43], 0, v[132:133]
	s_add_i32 m0, s77, 0xe000
	s_nop 0
	global_load_lds_dwordx4 v[138:139], off
	s_waitcnt lgkmcnt(8)
	s_barrier
	s_waitcnt lgkmcnt(0)
	s_setprio 1
	s_waitcnt lgkmcnt(0)
	v_mfma_f32_16x16x32_bf16 v[124:127], v[134:137], v[158:161], v[124:127]
	v_mfma_f32_16x16x32_bf16 v[120:123], v[150:153], v[158:161], v[120:123]
	v_mfma_f32_16x16x32_bf16 v[108:111], v[134:137], v[166:169], v[108:111]
	v_mfma_f32_16x16x32_bf16 v[104:107], v[150:153], v[166:169], v[104:107]
	v_mfma_f32_16x16x32_bf16 v[92:95], v[134:137], v[182:185], v[92:95]
	v_mfma_f32_16x16x32_bf16 v[88:91], v[150:153], v[182:185], v[88:91]
	v_mfma_f32_16x16x32_bf16 v[76:79], v[134:137], v[208:211], v[76:79]
	v_mfma_f32_16x16x32_bf16 v[72:75], v[150:153], v[208:211], v[72:75]
	v_mfma_f32_16x16x32_bf16 v[124:127], v[142:145], v[162:165], v[124:127]
	v_mfma_f32_16x16x32_bf16 v[120:123], v[154:157], v[162:165], v[120:123]
	v_mfma_f32_16x16x32_bf16 v[108:111], v[142:145], v[170:173], v[108:111]
	v_mfma_f32_16x16x32_bf16 v[104:107], v[154:157], v[170:173], v[104:107]
	v_mfma_f32_16x16x32_bf16 v[92:95], v[142:145], v[200:203], v[92:95]
	v_mfma_f32_16x16x32_bf16 v[88:91], v[154:157], v[200:203], v[88:91]
	v_mfma_f32_16x16x32_bf16 v[76:79], v[142:145], v[212:215], v[76:79]
	v_mfma_f32_16x16x32_bf16 v[72:75], v[154:157], v[212:215], v[72:75]
	s_setprio 0
	s_barrier
	s_add_i32 s1, 0, 0x14000
	v_add_u32_e32 v138, s1, v141
	s_add_i32 s2, s3, s75
	ds_read_b128 v[216:219], v138
	ds_read_b128 v[220:223], v138 offset:1024
	ds_read_b128 v[224:227], v138 offset:2048
	ds_read_b128 v[228:231], v138 offset:3072
	v_lshl_add_u64 v[138:139], s[70:71], 0, v[176:177]
	s_mov_b32 m0, s2
	v_lshl_add_u64 v[174:175], s[70:71], 0, v[128:129]
	global_load_lds_dwordx4 v[138:139], off
	s_add_i32 m0, s2, 0x2000
	s_nop 0
	global_load_lds_dwordx4 v[174:175], off
	s_barrier
	s_waitcnt lgkmcnt(0)
	s_setprio 1
	s_waitcnt lgkmcnt(0)
	v_mfma_f32_16x16x32_bf16 v[116:119], v[216:219], v[158:161], v[116:119]
	v_mfma_f32_16x16x32_bf16 v[112:115], v[224:227], v[158:161], v[112:115]
	v_mfma_f32_16x16x32_bf16 v[100:103], v[216:219], v[166:169], v[100:103]
	v_mfma_f32_16x16x32_bf16 v[96:99], v[224:227], v[166:169], v[96:99]
	v_mfma_f32_16x16x32_bf16 v[84:87], v[216:219], v[182:185], v[84:87]
	v_mfma_f32_16x16x32_bf16 v[80:83], v[224:227], v[182:185], v[80:83]
	v_mfma_f32_16x16x32_bf16 v[68:71], v[216:219], v[208:211], v[68:71]
	v_mfma_f32_16x16x32_bf16 v[64:67], v[224:227], v[208:211], v[64:67]
	v_mfma_f32_16x16x32_bf16 v[116:119], v[220:223], v[162:165], v[116:119]
	v_mfma_f32_16x16x32_bf16 v[112:115], v[228:231], v[162:165], v[112:115]
	v_mfma_f32_16x16x32_bf16 v[100:103], v[220:223], v[170:173], v[100:103]
	v_mfma_f32_16x16x32_bf16 v[96:99], v[228:231], v[170:173], v[96:99]
	v_mfma_f32_16x16x32_bf16 v[84:87], v[220:223], v[200:203], v[84:87]
	v_mfma_f32_16x16x32_bf16 v[80:83], v[228:231], v[200:203], v[80:83]
	v_mfma_f32_16x16x32_bf16 v[68:71], v[220:223], v[212:215], v[68:71]
	v_mfma_f32_16x16x32_bf16 v[64:67], v[228:231], v[212:215], v[64:67]
	s_setprio 0
	s_mov_b32 m0, s77
	v_lshl_add_u64 v[186:187], s[72:73], 0, v[176:177]
	s_barrier
	ds_read_b128 v[158:161], v149 offset:16384
	ds_read_b128 v[162:165], v149 offset:17408
	ds_read_b128 v[166:169], v149 offset:18432
	ds_read_b128 v[170:173], v149 offset:19456
	ds_read_b128 v[182:185], v149 offset:20480
	ds_read_b128 v[200:203], v149 offset:21504
	ds_read_b128 v[208:211], v149 offset:22528
	ds_read_b128 v[212:215], v149 offset:23552
	global_load_lds_dwordx4 v[186:187], off
	v_lshl_add_u64 v[190:191], s[72:73], 0, v[128:129]
	s_mov_b32 m0, s78
	s_nop 0
	global_load_lds_dwordx4 v[190:191], off
	s_barrier
	s_waitcnt lgkmcnt(0)
	s_setprio 1
	s_waitcnt lgkmcnt(0)
	v_mfma_f32_16x16x32_bf16 v[60:63], v[134:137], v[158:161], v[60:63]
	v_mfma_f32_16x16x32_bf16 v[56:59], v[150:153], v[158:161], v[56:59]
	v_mfma_f32_16x16x32_bf16 v[44:47], v[134:137], v[166:169], v[44:47]
	v_mfma_f32_16x16x32_bf16 v[40:43], v[150:153], v[166:169], v[40:43]
	v_mfma_f32_16x16x32_bf16 v[28:31], v[134:137], v[182:185], v[28:31]
	v_mfma_f32_16x16x32_bf16 v[24:27], v[150:153], v[182:185], v[24:27]
	v_mfma_f32_16x16x32_bf16 v[12:15], v[134:137], v[208:211], v[12:15]
	v_mfma_f32_16x16x32_bf16 v[8:11], v[150:153], v[208:211], v[8:11]
	v_mfma_f32_16x16x32_bf16 v[60:63], v[142:145], v[162:165], v[60:63]
	v_mfma_f32_16x16x32_bf16 v[56:59], v[154:157], v[162:165], v[56:59]
	v_mfma_f32_16x16x32_bf16 v[44:47], v[142:145], v[170:173], v[44:47]
	v_mfma_f32_16x16x32_bf16 v[40:43], v[154:157], v[170:173], v[40:43]
	v_mfma_f32_16x16x32_bf16 v[28:31], v[142:145], v[200:203], v[28:31]
	v_mfma_f32_16x16x32_bf16 v[24:27], v[154:157], v[200:203], v[24:27]
	v_mfma_f32_16x16x32_bf16 v[12:15], v[142:145], v[212:215], v[12:15]
	v_mfma_f32_16x16x32_bf16 v[8:11], v[154:157], v[212:215], v[8:11]
	s_setprio 0
	s_barrier
	s_add_u32 s2, s70, 0x80000
	s_addc_u32 s3, s71, 0
	s_add_i32 s1, s1, s75
	v_lshl_add_u64 v[134:135], s[2:3], 0, v[176:177]
	s_mov_b32 m0, s1
	s_nop 0
	global_load_lds_dwordx4 v[134:135], off
	v_lshl_add_u64 v[134:135], s[2:3], 0, v[128:129]
	s_add_i32 m0, s1, 0x2000
	s_nop 0
	global_load_lds_dwordx4 v[134:135], off
	s_waitcnt vmcnt(6)
	s_barrier
	s_setprio 1
	v_mfma_f32_16x16x32_bf16 v[52:55], v[216:219], v[158:161], v[52:55]
	v_mfma_f32_16x16x32_bf16 v[48:51], v[224:227], v[158:161], v[48:51]
	v_mfma_f32_16x16x32_bf16 v[36:39], v[216:219], v[166:169], v[36:39]
	v_mfma_f32_16x16x32_bf16 v[32:35], v[224:227], v[166:169], v[32:35]
	v_mfma_f32_16x16x32_bf16 v[20:23], v[216:219], v[182:185], v[20:23]
	v_mfma_f32_16x16x32_bf16 v[16:19], v[224:227], v[182:185], v[16:19]
	v_mfma_f32_16x16x32_bf16 v[4:7], v[216:219], v[208:211], v[4:7]
	v_mfma_f32_16x16x32_bf16 v[0:3], v[224:227], v[208:211], v[0:3]
	v_mfma_f32_16x16x32_bf16 v[52:55], v[220:223], v[162:165], v[52:55]
	v_mfma_f32_16x16x32_bf16 v[48:51], v[228:231], v[162:165], v[48:51]
	v_mfma_f32_16x16x32_bf16 v[36:39], v[220:223], v[170:173], v[36:39]
	v_mfma_f32_16x16x32_bf16 v[32:35], v[228:231], v[170:173], v[32:35]
	v_mfma_f32_16x16x32_bf16 v[20:23], v[220:223], v[200:203], v[20:23]
	v_mfma_f32_16x16x32_bf16 v[16:19], v[228:231], v[200:203], v[16:19]
	v_mfma_f32_16x16x32_bf16 v[4:7], v[220:223], v[212:215], v[4:7]
	v_mfma_f32_16x16x32_bf16 v[0:3], v[228:231], v[212:215], v[0:3]
	s_setprio 0
	s_add_i32 s1, 0, 0x18000
	v_add_u32_e32 v140, s1, v141
	s_barrier
	ds_read_b128 v[134:137], v140
	ds_read_b128 v[142:145], v140 offset:1024
	ds_read_b128 v[150:153], v140 offset:2048
	ds_read_b128 v[154:157], v140 offset:3072
	s_add_u32 s2, s72, 0x80000
	s_addc_u32 s3, s73, 0
	s_mov_b32 m0, s79
	v_lshl_add_u64 v[194:195], s[2:3], 0, v[176:177]
	ds_read_b128 v[158:161], v149 offset:32768
	ds_read_b128 v[162:165], v149 offset:33792
	ds_read_b128 v[166:169], v149 offset:34816
	ds_read_b128 v[170:173], v149 offset:35840
	ds_read_b128 v[182:185], v149 offset:36864
	ds_read_b128 v[200:203], v149 offset:37888
	ds_read_b128 v[208:211], v149 offset:38912
	ds_read_b128 v[212:215], v149 offset:39936
	global_load_lds_dwordx4 v[194:195], off
	v_lshl_add_u64 v[194:195], s[2:3], 0, v[128:129]
	s_mov_b32 m0, s80
	s_nop 0
	global_load_lds_dwordx4 v[194:195], off
	s_waitcnt lgkmcnt(8)
	s_barrier
	s_waitcnt lgkmcnt(0)
	s_setprio 1
	s_waitcnt lgkmcnt(0)
	v_mfma_f32_16x16x32_bf16 v[124:127], v[134:137], v[158:161], v[124:127]
	v_mfma_f32_16x16x32_bf16 v[120:123], v[150:153], v[158:161], v[120:123]
	v_mfma_f32_16x16x32_bf16 v[108:111], v[134:137], v[166:169], v[108:111]
	v_mfma_f32_16x16x32_bf16 v[104:107], v[150:153], v[166:169], v[104:107]
	v_mfma_f32_16x16x32_bf16 v[92:95], v[134:137], v[182:185], v[92:95]
	v_mfma_f32_16x16x32_bf16 v[88:91], v[150:153], v[182:185], v[88:91]
	v_mfma_f32_16x16x32_bf16 v[76:79], v[134:137], v[208:211], v[76:79]
	v_mfma_f32_16x16x32_bf16 v[72:75], v[150:153], v[208:211], v[72:75]
	v_mfma_f32_16x16x32_bf16 v[124:127], v[142:145], v[162:165], v[124:127]
	v_mfma_f32_16x16x32_bf16 v[120:123], v[154:157], v[162:165], v[120:123]
	v_mfma_f32_16x16x32_bf16 v[108:111], v[142:145], v[170:173], v[108:111]
	v_mfma_f32_16x16x32_bf16 v[104:107], v[154:157], v[170:173], v[104:107]
	v_mfma_f32_16x16x32_bf16 v[92:95], v[142:145], v[200:203], v[92:95]
	v_mfma_f32_16x16x32_bf16 v[88:91], v[154:157], v[200:203], v[88:91]
	v_mfma_f32_16x16x32_bf16 v[76:79], v[142:145], v[212:215], v[76:79]
	v_mfma_f32_16x16x32_bf16 v[72:75], v[154:157], v[212:215], v[72:75]
	s_setprio 0
	s_barrier
	s_add_i32 s12, 0, 0x1c000
	s_add_i32 s1, s1, s75
	v_add_u32_e32 v140, s12, v141
	v_lshl_add_u64 v[138:139], v[138:139], 0, s[20:21]
	s_mov_b32 m0, s1
	ds_read_b128 v[216:219], v140
	ds_read_b128 v[220:223], v140 offset:1024
	ds_read_b128 v[224:227], v140 offset:2048
	ds_read_b128 v[228:231], v140 offset:3072
	global_load_lds_dwordx4 v[138:139], off
	v_lshl_add_u64 v[138:139], v[174:175], 0, s[20:21]
	s_add_i32 m0, s1, 0x2000
	s_nop 0
	global_load_lds_dwordx4 v[138:139], off
	s_barrier
	s_waitcnt lgkmcnt(0)
	s_setprio 1
	s_waitcnt lgkmcnt(0)
	v_mfma_f32_16x16x32_bf16 v[116:119], v[216:219], v[158:161], v[116:119]
	v_mfma_f32_16x16x32_bf16 v[112:115], v[224:227], v[158:161], v[112:115]
	v_mfma_f32_16x16x32_bf16 v[100:103], v[216:219], v[166:169], v[100:103]
	v_mfma_f32_16x16x32_bf16 v[96:99], v[224:227], v[166:169], v[96:99]
	v_mfma_f32_16x16x32_bf16 v[84:87], v[216:219], v[182:185], v[84:87]
	v_mfma_f32_16x16x32_bf16 v[80:83], v[224:227], v[182:185], v[80:83]
	v_mfma_f32_16x16x32_bf16 v[68:71], v[216:219], v[208:211], v[68:71]
	v_mfma_f32_16x16x32_bf16 v[64:67], v[224:227], v[208:211], v[64:67]
	v_mfma_f32_16x16x32_bf16 v[116:119], v[220:223], v[162:165], v[116:119]
	v_mfma_f32_16x16x32_bf16 v[112:115], v[228:231], v[162:165], v[112:115]
	v_mfma_f32_16x16x32_bf16 v[100:103], v[220:223], v[170:173], v[100:103]
	v_mfma_f32_16x16x32_bf16 v[96:99], v[228:231], v[170:173], v[96:99]
	v_mfma_f32_16x16x32_bf16 v[84:87], v[220:223], v[200:203], v[84:87]
	v_mfma_f32_16x16x32_bf16 v[80:83], v[228:231], v[200:203], v[80:83]
	v_mfma_f32_16x16x32_bf16 v[68:71], v[220:223], v[212:215], v[68:71]
	v_mfma_f32_16x16x32_bf16 v[64:67], v[228:231], v[212:215], v[64:67]
	s_setprio 0
	s_mov_b32 m0, s83
	v_lshl_add_u64 v[138:139], v[186:187], 0, s[20:21]
	s_barrier
	ds_read_b128 v[158:161], v149 offset:49152
	ds_read_b128 v[162:165], v149 offset:50176
	ds_read_b128 v[166:169], v149 offset:51200
	ds_read_b128 v[170:173], v149 offset:52224
	ds_read_b128 v[182:185], v149 offset:53248
	ds_read_b128 v[200:203], v149 offset:54272
	ds_read_b128 v[208:211], v149 offset:55296
	ds_read_b128 v[212:215], v149 offset:56320
	global_load_lds_dwordx4 v[138:139], off
	v_lshl_add_u64 v[138:139], v[190:191], 0, s[20:21]
	s_mov_b32 m0, s74
	s_nop 0
	global_load_lds_dwordx4 v[138:139], off
	s_barrier
	s_waitcnt lgkmcnt(0)
	s_setprio 1
	s_waitcnt lgkmcnt(0)
	v_mfma_f32_16x16x32_bf16 v[60:63], v[134:137], v[158:161], v[60:63]
	v_mfma_f32_16x16x32_bf16 v[56:59], v[150:153], v[158:161], v[56:59]
	v_mfma_f32_16x16x32_bf16 v[44:47], v[134:137], v[166:169], v[44:47]
	v_mfma_f32_16x16x32_bf16 v[40:43], v[150:153], v[166:169], v[40:43]
	v_mfma_f32_16x16x32_bf16 v[28:31], v[134:137], v[182:185], v[28:31]
	v_mfma_f32_16x16x32_bf16 v[24:27], v[150:153], v[182:185], v[24:27]
	v_mfma_f32_16x16x32_bf16 v[12:15], v[134:137], v[208:211], v[12:15]
	v_mfma_f32_16x16x32_bf16 v[8:11], v[150:153], v[208:211], v[8:11]
	v_mfma_f32_16x16x32_bf16 v[60:63], v[142:145], v[162:165], v[60:63]
	v_mfma_f32_16x16x32_bf16 v[56:59], v[154:157], v[162:165], v[56:59]
	v_mfma_f32_16x16x32_bf16 v[44:47], v[142:145], v[170:173], v[44:47]
	v_mfma_f32_16x16x32_bf16 v[40:43], v[154:157], v[170:173], v[40:43]
	v_mfma_f32_16x16x32_bf16 v[28:31], v[142:145], v[200:203], v[28:31]
	v_mfma_f32_16x16x32_bf16 v[24:27], v[154:157], v[200:203], v[24:27]
	v_mfma_f32_16x16x32_bf16 v[12:15], v[142:145], v[212:215], v[12:15]
	v_mfma_f32_16x16x32_bf16 v[8:11], v[154:157], v[212:215], v[8:11]
	s_setprio 0
	s_barrier
	s_add_u32 s2, s70, 0x80080
	s_addc_u32 s3, s71, 0
	s_add_i32 s1, s12, s75
	v_lshl_add_u64 v[134:135], s[2:3], 0, v[176:177]
	s_mov_b32 m0, s1
	s_nop 0
	global_load_lds_dwordx4 v[134:135], off
	v_lshl_add_u64 v[134:135], s[2:3], 0, v[128:129]
	s_add_i32 m0, s1, 0x2000
	s_nop 0
	global_load_lds_dwordx4 v[134:135], off
	s_waitcnt vmcnt(6)
	s_barrier
	s_setprio 1
	v_mfma_f32_16x16x32_bf16 v[52:55], v[216:219], v[158:161], v[52:55]
	v_mfma_f32_16x16x32_bf16 v[48:51], v[224:227], v[158:161], v[48:51]
	v_mfma_f32_16x16x32_bf16 v[36:39], v[216:219], v[166:169], v[36:39]
	v_mfma_f32_16x16x32_bf16 v[32:35], v[224:227], v[166:169], v[32:35]
	v_mfma_f32_16x16x32_bf16 v[20:23], v[216:219], v[182:185], v[20:23]
	v_mfma_f32_16x16x32_bf16 v[16:19], v[224:227], v[182:185], v[16:19]
	v_mfma_f32_16x16x32_bf16 v[4:7], v[216:219], v[208:211], v[4:7]
	v_mfma_f32_16x16x32_bf16 v[0:3], v[224:227], v[208:211], v[0:3]
	v_mfma_f32_16x16x32_bf16 v[52:55], v[220:223], v[162:165], v[52:55]
	v_mfma_f32_16x16x32_bf16 v[48:51], v[228:231], v[162:165], v[48:51]
	v_mfma_f32_16x16x32_bf16 v[36:39], v[220:223], v[170:173], v[36:39]
	v_mfma_f32_16x16x32_bf16 v[32:35], v[228:231], v[170:173], v[32:35]
	v_mfma_f32_16x16x32_bf16 v[20:23], v[220:223], v[200:203], v[20:23]
	v_mfma_f32_16x16x32_bf16 v[16:19], v[228:231], v[200:203], v[16:19]
	v_mfma_f32_16x16x32_bf16 v[4:7], v[220:223], v[212:215], v[4:7]
	v_mfma_f32_16x16x32_bf16 v[0:3], v[228:231], v[212:215], v[0:3]
	s_setprio 0
	s_add_i32 s88, s88, 2
	s_add_u32 s42, s42, 0x100
	s_addc_u32 s43, s43, 0
	s_add_u32 s61, s61, 0x100
	s_addc_u32 s87, s87, 0
	s_cmp_gt_u32 s88, 29
	s_barrier
	s_cbranch_scc0 .LBB0_647
	v_and_b32_e32 v198, 15, v147
	v_ashrrev_i32_e32 v252, 4, v147
	s_lshl_b32 s1, s52, 8
	s_add_i32 s1, s1, s81
	v_or_b32_e32 v198, s1, v198
	s_lshl_b32 s1, s49, 8
	s_or_b32 s1, s1, s82
	v_lshl_add_u32 v140, v252, 2, s1
	v_lshl_add_u32 v140, v198, 11, v140
	v_lshlrev_b32_e32 v140, 1, v140
	v_lshlrev_b32_e32 v146, 5, v252
	v_lshl_add_u32 v146, v198, 7, v146
	s_lshr_b32 s1, s82, 5
	s_lshl2_add_u32 s1, s49, s1
	s_lshl_b32 s1, s1, 2
	v_lshl_add_u32 v198, v198, 7, s1
	v_readlane_b32 s98, v255, 1
	v_readlane_b32 s99, v255, 2
	s_mov_b32 s49, s46
	s_mov_b32 s52, s44
	s_mov_b64 s[70:71], s[68:69]
	s_movk_i32 s14, 0x3fff
	s_mov_b64 s[42:43], s[38:39]
	v_mov_b32_e32 v148, v146
	global_load_dwordx4 v[208:211], v148, s[16:17]
	global_load_dwordx4 v[212:215], v148, s[16:17] offset:16
	v_add_u32_e32 v188, 0x800, v146
	global_load_dwordx4 v[216:219], v188, s[16:17]
	global_load_dwordx4 v[220:223], v188, s[16:17] offset:16
	v_add_u32_e32 v192, 0x1000, v146
	global_load_dwordx4 v[224:227], v192, s[16:17]
	global_load_dwordx4 v[228:231], v192, s[16:17] offset:16
	v_add_u32_e32 v196, 0x1800, v146
	global_load_dwordx4 v[232:235], v196, s[16:17]
	global_load_dwordx4 v[236:239], v196, s[16:17] offset:16
	v_mov_b32_e32 v148, v140
	global_load_dwordx2 v[152:153], v148, s[58:59] offset:0
	global_load_dwordx2 v[154:155], v148, s[56:57] offset:0
	global_load_dwordx2 v[156:157], v148, s[58:59] offset:32
	global_load_dwordx2 v[158:159], v148, s[56:57] offset:32
	global_load_dwordx2 v[160:161], v148, s[58:59] offset:256
	global_load_dwordx2 v[162:163], v148, s[56:57] offset:256
	global_load_dwordx2 v[164:165], v148, s[58:59] offset:288
	global_load_dwordx2 v[166:167], v148, s[56:57] offset:288
	v_add_u32_e32 v188, 0x10000, v140
	global_load_dwordx2 v[168:169], v188, s[58:59] offset:0
	global_load_dwordx2 v[170:171], v188, s[56:57] offset:0
	global_load_dwordx2 v[172:173], v188, s[58:59] offset:32
	global_load_dwordx2 v[174:175], v188, s[56:57] offset:32
	global_load_dwordx2 v[240:241], v188, s[58:59] offset:256
	global_load_dwordx2 v[242:243], v188, s[56:57] offset:256
	global_load_dwordx2 v[244:245], v188, s[58:59] offset:288
	global_load_dwordx2 v[246:247], v188, s[56:57] offset:288
	v_add_u32_e32 v192, 0x20000, v140
	global_load_dwordx2 v[182:183], v192, s[58:59] offset:0
	global_load_dwordx2 v[184:185], v192, s[56:57] offset:0
	global_load_dwordx2 v[186:187], v192, s[58:59] offset:32
	global_load_dwordx2 v[200:201], v192, s[56:57] offset:32
	global_load_dwordx2 v[202:203], v192, s[58:59] offset:256
	global_load_dwordx2 v[204:205], v192, s[56:57] offset:256
	global_load_dwordx2 v[134:135], v192, s[58:59] offset:288
	global_load_dwordx2 v[136:137], v192, s[56:57] offset:288
	v_add_u32_e32 v196, 0x30000, v140
	global_load_dwordx2 v[138:139], v196, s[58:59] offset:0
	global_load_dwordx2 v[142:143], v196, s[56:57] offset:0
	global_load_dwordx2 v[144:145], v196, s[58:59] offset:32
	global_load_dwordx2 v[190:191], v196, s[56:57] offset:32
	global_load_dwordx2 v[194:195], v196, s[58:59] offset:256
	global_load_dwordx2 v[248:249], v196, s[56:57] offset:256
	global_load_dwordx2 v[150:151], v196, s[58:59] offset:288
	s_waitcnt vmcnt(31)
	v_add_f32_e32 v208, v208, v209
	v_add_f32_e32 v210, v210, v211
	v_add_f32_e32 v212, v212, v213
	v_add_f32_e32 v214, v214, v215
	v_add_f32_e32 v208, v208, v210
	v_add_f32_e32 v212, v212, v214
	v_add_f32_e32 v208, v208, v212
	v_add_f32_e32 v216, v216, v217
	v_add_f32_e32 v218, v218, v219
	v_add_f32_e32 v220, v220, v221
	v_add_f32_e32 v222, v222, v223
	v_add_f32_e32 v216, v216, v218
	v_add_f32_e32 v220, v220, v222
	v_add_f32_e32 v216, v216, v220
	v_add_f32_e32 v224, v224, v225
	v_add_f32_e32 v226, v226, v227
	v_add_f32_e32 v228, v228, v229
	v_add_f32_e32 v230, v230, v231
	v_add_f32_e32 v224, v224, v226
	v_add_f32_e32 v228, v228, v230
	v_add_f32_e32 v224, v224, v228
	v_add_f32_e32 v232, v232, v233
	v_add_f32_e32 v234, v234, v235
	v_add_f32_e32 v236, v236, v237
	v_add_f32_e32 v238, v238, v239
	v_add_f32_e32 v232, v232, v234
	v_add_f32_e32 v236, v236, v238
	v_add_f32_e32 v232, v232, v236
	ds_bpermute_b32 v209, v207, v208
	ds_bpermute_b32 v217, v207, v216
	ds_bpermute_b32 v225, v207, v224
	ds_bpermute_b32 v233, v207, v232
	s_waitcnt lgkmcnt(0)
	v_add_f32_e32 v208, v208, v209
	v_add_f32_e32 v216, v216, v217
	v_add_f32_e32 v224, v224, v225
	v_add_f32_e32 v232, v232, v233
	ds_bpermute_b32 v209, v206, v208
	ds_bpermute_b32 v217, v206, v216
	ds_bpermute_b32 v225, v206, v224
	ds_bpermute_b32 v233, v206, v232
	s_waitcnt lgkmcnt(0)
	v_add_f32_e32 v208, v208, v209
	v_add_f32_e32 v216, v216, v217
	v_add_f32_e32 v224, v224, v225
	v_add_f32_e32 v232, v232, v233
	v_mul_f32_e32 v208, 0x3a000000, v208
	v_add_f32_e32 v208, 0x358637bd, v208
	v_mul_f32_e32 v216, 0x3a000000, v216
	v_add_f32_e32 v216, 0x358637bd, v216
	v_mul_f32_e32 v224, 0x3a000000, v224
	v_add_f32_e32 v224, 0x358637bd, v224
	v_mul_f32_e32 v232, 0x3a000000, v232
	v_add_f32_e32 v232, 0x358637bd, v232
	v_rsq_f32_e32 v208, v208
	v_rsq_f32_e32 v216, v216
	v_rsq_f32_e32 v224, v224
	v_rsq_f32_e32 v232, v232
	s_nop 0
	v_mov_b32_e32 v209, v216
	v_mov_b32_e32 v210, v224
	v_mov_b32_e32 v211, v232
	v_add_u32_e32 v148, 0x30000, v140
	global_load_dwordx2 v[238:239], v148, s[56:57] offset:288
	s_waitcnt vmcnt(16)
	v_mov_b32_e32 v188, v140
	v_mul_f32_e32 v124, v124, v208
	v_mul_f32_e32 v125, v125, v208
	v_mul_f32_e32 v126, v126, v208
	v_mul_f32_e32 v127, v127, v208
	v_mul_f32_e32 v124, 0xbfb8aa3b, v124
	v_mul_f32_e32 v125, 0xbfb8aa3b, v125
	v_mul_f32_e32 v126, 0xbfb8aa3b, v126
	v_mul_f32_e32 v127, 0xbfb8aa3b, v127
	v_exp_f32_e32 v124, v124
	v_exp_f32_e32 v125, v125
	v_exp_f32_e32 v126, v126
	v_exp_f32_e32 v127, v127
	v_add_f32_e32 v124, 1.0, v124
	v_add_f32_e32 v125, 1.0, v125
	v_add_f32_e32 v126, 1.0, v126
	v_add_f32_e32 v127, 1.0, v127
	v_rcp_f32_e32 v220, v124
	v_rcp_f32_e32 v221, v125
	v_rcp_f32_e32 v222, v126
	v_rcp_f32_e32 v223, v127
	v_fma_f32 v224, -v124, v220, 1.0
	v_fma_f32 v225, -v125, v221, 1.0
	v_fma_f32 v226, -v126, v222, 1.0
	v_fma_f32 v227, -v127, v223, 1.0
	v_fma_f32 v124, v224, v220, v220
	v_fma_f32 v125, v225, v221, v221
	v_fma_f32 v126, v226, v222, v222
	v_fma_f32 v127, v227, v223, v223
	v_lshlrev_b32_e32 v230, 16, v152
	v_and_b32_e32 v152, 0xffff0000, v152
	v_lshlrev_b32_e32 v231, 16, v153
	v_and_b32_e32 v153, 0xffff0000, v153
	v_lshlrev_b32_e32 v232, 16, v154
	v_and_b32_e32 v154, 0xffff0000, v154
	v_lshlrev_b32_e32 v233, 16, v155
	v_and_b32_e32 v155, 0xffff0000, v155
	v_fma_f32 v124, v124, v232, v230
	v_fma_f32 v125, v125, v154, v152
	v_fma_f32 v126, v126, v233, v231
	v_fma_f32 v127, v127, v155, v153
	v_mul_f32_e32 v228, v124, v124
	v_fmac_f32_e32 v228, v125, v125
	v_fmac_f32_e32 v228, v126, v126
	v_fmac_f32_e32 v228, v127, v127
	v_cvt_pk_bf16_f32 v152, v124, v125
	v_cvt_pk_bf16_f32 v153, v126, v127
	global_store_dwordx2 v188, v[152:153], s[62:63] offset:0
	v_mul_f32_e32 v120, v120, v208
	v_mul_f32_e32 v121, v121, v208
	v_mul_f32_e32 v122, v122, v208
	v_mul_f32_e32 v123, v123, v208
	v_mul_f32_e32 v120, 0xbfb8aa3b, v120
	v_mul_f32_e32 v121, 0xbfb8aa3b, v121
	v_mul_f32_e32 v122, 0xbfb8aa3b, v122
	v_mul_f32_e32 v123, 0xbfb8aa3b, v123
	v_exp_f32_e32 v120, v120
	v_exp_f32_e32 v121, v121
	v_exp_f32_e32 v122, v122
	v_exp_f32_e32 v123, v123
	v_add_f32_e32 v120, 1.0, v120
	v_add_f32_e32 v121, 1.0, v121
	v_add_f32_e32 v122, 1.0, v122
	v_add_f32_e32 v123, 1.0, v123
	v_rcp_f32_e32 v220, v120
	v_rcp_f32_e32 v221, v121
	v_rcp_f32_e32 v222, v122
	v_rcp_f32_e32 v223, v123
	v_fma_f32 v224, -v120, v220, 1.0
	v_fma_f32 v225, -v121, v221, 1.0
	v_fma_f32 v226, -v122, v222, 1.0
	v_fma_f32 v227, -v123, v223, 1.0
	v_fma_f32 v120, v224, v220, v220
	v_fma_f32 v121, v225, v221, v221
	v_fma_f32 v122, v226, v222, v222
	v_fma_f32 v123, v227, v223, v223
	v_lshlrev_b32_e32 v230, 16, v156
	v_and_b32_e32 v156, 0xffff0000, v156
	v_lshlrev_b32_e32 v231, 16, v157
	v_and_b32_e32 v157, 0xffff0000, v157
	v_lshlrev_b32_e32 v232, 16, v158
	v_and_b32_e32 v158, 0xffff0000, v158
	v_lshlrev_b32_e32 v233, 16, v159
	v_and_b32_e32 v159, 0xffff0000, v159
	v_fma_f32 v120, v120, v232, v230
	v_fma_f32 v121, v121, v158, v156
	v_fma_f32 v122, v122, v233, v231
	v_fma_f32 v123, v123, v159, v157
	v_fmac_f32_e32 v228, v120, v120
	v_fmac_f32_e32 v228, v121, v121
	v_fmac_f32_e32 v228, v122, v122
	v_fmac_f32_e32 v228, v123, v123
	v_cvt_pk_bf16_f32 v156, v120, v121
	v_cvt_pk_bf16_f32 v157, v122, v123
	global_store_dwordx2 v188, v[156:157], s[62:63] offset:32
	v_mul_f32_e32 v116, v116, v208
	v_mul_f32_e32 v117, v117, v208
	v_mul_f32_e32 v118, v118, v208
	v_mul_f32_e32 v119, v119, v208
	v_mul_f32_e32 v116, 0xbfb8aa3b, v116
	v_mul_f32_e32 v117, 0xbfb8aa3b, v117
	v_mul_f32_e32 v118, 0xbfb8aa3b, v118
	v_mul_f32_e32 v119, 0xbfb8aa3b, v119
	v_exp_f32_e32 v116, v116
	v_exp_f32_e32 v117, v117
	v_exp_f32_e32 v118, v118
	v_exp_f32_e32 v119, v119
	v_add_f32_e32 v116, 1.0, v116
	v_add_f32_e32 v117, 1.0, v117
	v_add_f32_e32 v118, 1.0, v118
	v_add_f32_e32 v119, 1.0, v119
	v_rcp_f32_e32 v220, v116
	v_rcp_f32_e32 v221, v117
	v_rcp_f32_e32 v222, v118
	v_rcp_f32_e32 v223, v119
	v_fma_f32 v224, -v116, v220, 1.0
	v_fma_f32 v225, -v117, v221, 1.0
	v_fma_f32 v226, -v118, v222, 1.0
	v_fma_f32 v227, -v119, v223, 1.0
	v_fma_f32 v116, v224, v220, v220
	v_fma_f32 v117, v225, v221, v221
	v_fma_f32 v118, v226, v222, v222
	v_fma_f32 v119, v227, v223, v223
	v_lshlrev_b32_e32 v230, 16, v160
	v_and_b32_e32 v160, 0xffff0000, v160
	v_lshlrev_b32_e32 v231, 16, v161
	v_and_b32_e32 v161, 0xffff0000, v161
	v_lshlrev_b32_e32 v232, 16, v162
	v_and_b32_e32 v162, 0xffff0000, v162
	v_lshlrev_b32_e32 v233, 16, v163
	v_and_b32_e32 v163, 0xffff0000, v163
	v_fma_f32 v116, v116, v232, v230
	v_fma_f32 v117, v117, v162, v160
	v_fma_f32 v118, v118, v233, v231
	v_fma_f32 v119, v119, v163, v161
	v_fmac_f32_e32 v228, v116, v116
	v_fmac_f32_e32 v228, v117, v117
	v_fmac_f32_e32 v228, v118, v118
	v_fmac_f32_e32 v228, v119, v119
	v_cvt_pk_bf16_f32 v160, v116, v117
	v_cvt_pk_bf16_f32 v161, v118, v119
	global_store_dwordx2 v188, v[160:161], s[62:63] offset:256
	v_mul_f32_e32 v112, v112, v208
	v_mul_f32_e32 v113, v113, v208
	v_mul_f32_e32 v114, v114, v208
	v_mul_f32_e32 v115, v115, v208
	v_mul_f32_e32 v112, 0xbfb8aa3b, v112
	v_mul_f32_e32 v113, 0xbfb8aa3b, v113
	v_mul_f32_e32 v114, 0xbfb8aa3b, v114
	v_mul_f32_e32 v115, 0xbfb8aa3b, v115
	v_exp_f32_e32 v112, v112
	v_exp_f32_e32 v113, v113
	v_exp_f32_e32 v114, v114
	v_exp_f32_e32 v115, v115
	v_add_f32_e32 v112, 1.0, v112
	v_add_f32_e32 v113, 1.0, v113
	v_add_f32_e32 v114, 1.0, v114
	v_add_f32_e32 v115, 1.0, v115
	v_rcp_f32_e32 v220, v112
	v_rcp_f32_e32 v221, v113
	v_rcp_f32_e32 v222, v114
	v_rcp_f32_e32 v223, v115
	v_fma_f32 v224, -v112, v220, 1.0
	v_fma_f32 v225, -v113, v221, 1.0
	v_fma_f32 v226, -v114, v222, 1.0
	v_fma_f32 v227, -v115, v223, 1.0
	v_fma_f32 v112, v224, v220, v220
	v_fma_f32 v113, v225, v221, v221
	v_fma_f32 v114, v226, v222, v222
	v_fma_f32 v115, v227, v223, v223
	v_lshlrev_b32_e32 v230, 16, v164
	v_and_b32_e32 v164, 0xffff0000, v164
	v_lshlrev_b32_e32 v231, 16, v165
	v_and_b32_e32 v165, 0xffff0000, v165
	v_lshlrev_b32_e32 v232, 16, v166
	v_and_b32_e32 v166, 0xffff0000, v166
	v_lshlrev_b32_e32 v233, 16, v167
	v_and_b32_e32 v167, 0xffff0000, v167
	v_fma_f32 v112, v112, v232, v230
	v_fma_f32 v113, v113, v166, v164
	v_fma_f32 v114, v114, v233, v231
	v_fma_f32 v115, v115, v167, v165
	v_fmac_f32_e32 v228, v112, v112
	v_fmac_f32_e32 v228, v113, v113
	v_fmac_f32_e32 v228, v114, v114
	v_fmac_f32_e32 v228, v115, v115
	v_cvt_pk_bf16_f32 v164, v112, v113
	v_cvt_pk_bf16_f32 v165, v114, v115
	global_store_dwordx2 v188, v[164:165], s[62:63] offset:288
	ds_bpermute_b32 v229, v207, v228
	s_waitcnt lgkmcnt(0)
	v_add_f32_e32 v228, v228, v229
	ds_bpermute_b32 v229, v206, v228
	s_waitcnt lgkmcnt(0)
	v_add_f32_e32 v228, v228, v229
	v_mov_b32_e32 v252, v198
	v_cmp_gt_u32_e32 vcc, 16, v147
	s_and_saveexec_b64 s[2:3], vcc
	global_store_dword v252, v228, s[98:99]
	s_or_b64 exec, exec, s[2:3]
	v_add_u32_e32 v192, 0x10000, v140
	v_mul_f32_e32 v108, v108, v209
	v_mul_f32_e32 v109, v109, v209
	v_mul_f32_e32 v110, v110, v209
	v_mul_f32_e32 v111, v111, v209
	v_mul_f32_e32 v108, 0xbfb8aa3b, v108
	v_mul_f32_e32 v109, 0xbfb8aa3b, v109
	v_mul_f32_e32 v110, 0xbfb8aa3b, v110
	v_mul_f32_e32 v111, 0xbfb8aa3b, v111
	v_exp_f32_e32 v108, v108
	v_exp_f32_e32 v109, v109
	v_exp_f32_e32 v110, v110
	v_exp_f32_e32 v111, v111
	v_add_f32_e32 v108, 1.0, v108
	v_add_f32_e32 v109, 1.0, v109
	v_add_f32_e32 v110, 1.0, v110
	v_add_f32_e32 v111, 1.0, v111
	v_rcp_f32_e32 v220, v108
	v_rcp_f32_e32 v221, v109
	v_rcp_f32_e32 v222, v110
	v_rcp_f32_e32 v223, v111
	v_fma_f32 v224, -v108, v220, 1.0
	v_fma_f32 v225, -v109, v221, 1.0
	v_fma_f32 v226, -v110, v222, 1.0
	v_fma_f32 v227, -v111, v223, 1.0
	v_fma_f32 v108, v224, v220, v220
	v_fma_f32 v109, v225, v221, v221
	v_fma_f32 v110, v226, v222, v222
	v_fma_f32 v111, v227, v223, v223
	v_lshlrev_b32_e32 v230, 16, v168
	v_and_b32_e32 v168, 0xffff0000, v168
	v_lshlrev_b32_e32 v231, 16, v169
	v_and_b32_e32 v169, 0xffff0000, v169
	v_lshlrev_b32_e32 v232, 16, v170
	v_and_b32_e32 v170, 0xffff0000, v170
	v_lshlrev_b32_e32 v233, 16, v171
	v_and_b32_e32 v171, 0xffff0000, v171
	v_fma_f32 v108, v108, v232, v230
	v_fma_f32 v109, v109, v170, v168
	v_fma_f32 v110, v110, v233, v231
	v_fma_f32 v111, v111, v171, v169
	v_mul_f32_e32 v228, v108, v108
	v_fmac_f32_e32 v228, v109, v109
	v_fmac_f32_e32 v228, v110, v110
	v_fmac_f32_e32 v228, v111, v111
	v_cvt_pk_bf16_f32 v168, v108, v109
	v_cvt_pk_bf16_f32 v169, v110, v111
	global_store_dwordx2 v192, v[168:169], s[62:63] offset:0
	v_mul_f32_e32 v104, v104, v209
	v_mul_f32_e32 v105, v105, v209
	v_mul_f32_e32 v106, v106, v209
	v_mul_f32_e32 v107, v107, v209
	v_mul_f32_e32 v104, 0xbfb8aa3b, v104
	v_mul_f32_e32 v105, 0xbfb8aa3b, v105
	v_mul_f32_e32 v106, 0xbfb8aa3b, v106
	v_mul_f32_e32 v107, 0xbfb8aa3b, v107
	v_exp_f32_e32 v104, v104
	v_exp_f32_e32 v105, v105
	v_exp_f32_e32 v106, v106
	v_exp_f32_e32 v107, v107
	v_add_f32_e32 v104, 1.0, v104
	v_add_f32_e32 v105, 1.0, v105
	v_add_f32_e32 v106, 1.0, v106
	v_add_f32_e32 v107, 1.0, v107
	v_rcp_f32_e32 v220, v104
	v_rcp_f32_e32 v221, v105
	v_rcp_f32_e32 v222, v106
	v_rcp_f32_e32 v223, v107
	v_fma_f32 v224, -v104, v220, 1.0
	v_fma_f32 v225, -v105, v221, 1.0
	v_fma_f32 v226, -v106, v222, 1.0
	v_fma_f32 v227, -v107, v223, 1.0
	v_fma_f32 v104, v224, v220, v220
	v_fma_f32 v105, v225, v221, v221
	v_fma_f32 v106, v226, v222, v222
	v_fma_f32 v107, v227, v223, v223
	v_lshlrev_b32_e32 v230, 16, v172
	v_and_b32_e32 v172, 0xffff0000, v172
	v_lshlrev_b32_e32 v231, 16, v173
	v_and_b32_e32 v173, 0xffff0000, v173
	v_lshlrev_b32_e32 v232, 16, v174
	v_and_b32_e32 v174, 0xffff0000, v174
	v_lshlrev_b32_e32 v233, 16, v175
	v_and_b32_e32 v175, 0xffff0000, v175
	v_fma_f32 v104, v104, v232, v230
	v_fma_f32 v105, v105, v174, v172
	v_fma_f32 v106, v106, v233, v231
	v_fma_f32 v107, v107, v175, v173
	v_fmac_f32_e32 v228, v104, v104
	v_fmac_f32_e32 v228, v105, v105
	v_fmac_f32_e32 v228, v106, v106
	v_fmac_f32_e32 v228, v107, v107
	v_cvt_pk_bf16_f32 v172, v104, v105
	v_cvt_pk_bf16_f32 v173, v106, v107
	global_store_dwordx2 v192, v[172:173], s[62:63] offset:32
	v_mul_f32_e32 v100, v100, v209
	v_mul_f32_e32 v101, v101, v209
	v_mul_f32_e32 v102, v102, v209
	v_mul_f32_e32 v103, v103, v209
	v_mul_f32_e32 v100, 0xbfb8aa3b, v100
	v_mul_f32_e32 v101, 0xbfb8aa3b, v101
	v_mul_f32_e32 v102, 0xbfb8aa3b, v102
	v_mul_f32_e32 v103, 0xbfb8aa3b, v103
	v_exp_f32_e32 v100, v100
	v_exp_f32_e32 v101, v101
	v_exp_f32_e32 v102, v102
	v_exp_f32_e32 v103, v103
	v_add_f32_e32 v100, 1.0, v100
	v_add_f32_e32 v101, 1.0, v101
	v_add_f32_e32 v102, 1.0, v102
	v_add_f32_e32 v103, 1.0, v103
	v_rcp_f32_e32 v220, v100
	v_rcp_f32_e32 v221, v101
	v_rcp_f32_e32 v222, v102
	v_rcp_f32_e32 v223, v103
	v_fma_f32 v224, -v100, v220, 1.0
	v_fma_f32 v225, -v101, v221, 1.0
	v_fma_f32 v226, -v102, v222, 1.0
	v_fma_f32 v227, -v103, v223, 1.0
	v_fma_f32 v100, v224, v220, v220
	v_fma_f32 v101, v225, v221, v221
	v_fma_f32 v102, v226, v222, v222
	v_fma_f32 v103, v227, v223, v223
	v_lshlrev_b32_e32 v230, 16, v240
	v_and_b32_e32 v240, 0xffff0000, v240
	v_lshlrev_b32_e32 v231, 16, v241
	v_and_b32_e32 v241, 0xffff0000, v241
	v_lshlrev_b32_e32 v232, 16, v242
	v_and_b32_e32 v242, 0xffff0000, v242
	v_lshlrev_b32_e32 v233, 16, v243
	v_and_b32_e32 v243, 0xffff0000, v243
	v_fma_f32 v100, v100, v232, v230
	v_fma_f32 v101, v101, v242, v240
	v_fma_f32 v102, v102, v233, v231
	v_fma_f32 v103, v103, v243, v241
	v_fmac_f32_e32 v228, v100, v100
	v_fmac_f32_e32 v228, v101, v101
	v_fmac_f32_e32 v228, v102, v102
	v_fmac_f32_e32 v228, v103, v103
	v_cvt_pk_bf16_f32 v240, v100, v101
	v_cvt_pk_bf16_f32 v241, v102, v103
	global_store_dwordx2 v192, v[240:241], s[62:63] offset:256
	v_mul_f32_e32 v96, v96, v209
	v_mul_f32_e32 v97, v97, v209
	v_mul_f32_e32 v98, v98, v209
	v_mul_f32_e32 v99, v99, v209
	v_mul_f32_e32 v96, 0xbfb8aa3b, v96
	v_mul_f32_e32 v97, 0xbfb8aa3b, v97
	v_mul_f32_e32 v98, 0xbfb8aa3b, v98
	v_mul_f32_e32 v99, 0xbfb8aa3b, v99
	v_exp_f32_e32 v96, v96
	v_exp_f32_e32 v97, v97
	v_exp_f32_e32 v98, v98
	v_exp_f32_e32 v99, v99
	v_add_f32_e32 v96, 1.0, v96
	v_add_f32_e32 v97, 1.0, v97
	v_add_f32_e32 v98, 1.0, v98
	v_add_f32_e32 v99, 1.0, v99
	v_rcp_f32_e32 v220, v96
	v_rcp_f32_e32 v221, v97
	v_rcp_f32_e32 v222, v98
	v_rcp_f32_e32 v223, v99
	v_fma_f32 v224, -v96, v220, 1.0
	v_fma_f32 v225, -v97, v221, 1.0
	v_fma_f32 v226, -v98, v222, 1.0
	v_fma_f32 v227, -v99, v223, 1.0
	v_fma_f32 v96, v224, v220, v220
	v_fma_f32 v97, v225, v221, v221
	v_fma_f32 v98, v226, v222, v222
	v_fma_f32 v99, v227, v223, v223
	v_lshlrev_b32_e32 v230, 16, v244
	v_and_b32_e32 v244, 0xffff0000, v244
	v_lshlrev_b32_e32 v231, 16, v245
	v_and_b32_e32 v245, 0xffff0000, v245
	v_lshlrev_b32_e32 v232, 16, v246
	v_and_b32_e32 v246, 0xffff0000, v246
	v_lshlrev_b32_e32 v233, 16, v247
	v_and_b32_e32 v247, 0xffff0000, v247
	v_fma_f32 v96, v96, v232, v230
	v_fma_f32 v97, v97, v246, v244
	v_fma_f32 v98, v98, v233, v231
	v_fma_f32 v99, v99, v247, v245
	v_fmac_f32_e32 v228, v96, v96
	v_fmac_f32_e32 v228, v97, v97
	v_fmac_f32_e32 v228, v98, v98
	v_fmac_f32_e32 v228, v99, v99
	v_cvt_pk_bf16_f32 v244, v96, v97
	v_cvt_pk_bf16_f32 v245, v98, v99
	global_store_dwordx2 v192, v[244:245], s[62:63] offset:288
	ds_bpermute_b32 v229, v207, v228
	s_waitcnt lgkmcnt(0)
	v_add_f32_e32 v228, v228, v229
	ds_bpermute_b32 v229, v206, v228
	s_waitcnt lgkmcnt(0)
	v_add_f32_e32 v228, v228, v229
	v_add_u32_e32 v252, 0x800, v198
	v_cmp_gt_u32_e32 vcc, 16, v147
	s_and_saveexec_b64 s[2:3], vcc
	global_store_dword v252, v228, s[98:99]
	s_or_b64 exec, exec, s[2:3]
	v_add_u32_e32 v196, 0x4000, v146
	global_load_dwordx4 v[96:99], v196, s[16:17]
	global_load_dwordx4 v[100:103], v196, s[16:17] offset:16
	v_add_u32_e32 v148, 0x4800, v146
	global_load_dwordx4 v[104:107], v148, s[16:17]
	global_load_dwordx4 v[108:111], v148, s[16:17] offset:16
	v_add_u32_e32 v188, 0x5000, v146
	global_load_dwordx4 v[112:115], v188, s[16:17]
	global_load_dwordx4 v[116:119], v188, s[16:17] offset:16
	v_add_u32_e32 v192, 0x5800, v146
	global_load_dwordx4 v[120:123], v192, s[16:17]
	global_load_dwordx4 v[124:127], v192, s[16:17] offset:16
	v_add_u32_e32 v196, 0x80000, v140
	global_load_dwordx2 v[152:153], v196, s[58:59] offset:0
	global_load_dwordx2 v[154:155], v196, s[56:57] offset:0
	global_load_dwordx2 v[156:157], v196, s[58:59] offset:32
	global_load_dwordx2 v[158:159], v196, s[56:57] offset:32
	global_load_dwordx2 v[160:161], v196, s[58:59] offset:256
	global_load_dwordx2 v[162:163], v196, s[56:57] offset:256
	global_load_dwordx2 v[164:165], v196, s[58:59] offset:288
	global_load_dwordx2 v[166:167], v196, s[56:57] offset:288
	v_add_u32_e32 v148, 0x90000, v140
	global_load_dwordx2 v[168:169], v148, s[58:59] offset:0
	global_load_dwordx2 v[170:171], v148, s[56:57] offset:0
	global_load_dwordx2 v[172:173], v148, s[58:59] offset:32
	global_load_dwordx2 v[174:175], v148, s[56:57] offset:32
	global_load_dwordx2 v[240:241], v148, s[58:59] offset:256
	global_load_dwordx2 v[242:243], v148, s[56:57] offset:256
	global_load_dwordx2 v[244:245], v148, s[58:59] offset:288
	global_load_dwordx2 v[246:247], v148, s[56:57] offset:288
	s_waitcnt vmcnt(34)
	v_add_u32_e32 v188, 0x20000, v140
	v_mul_f32_e32 v92, v92, v210
	v_mul_f32_e32 v93, v93, v210
	v_mul_f32_e32 v94, v94, v210
	v_mul_f32_e32 v95, v95, v210
	v_mul_f32_e32 v92, 0xbfb8aa3b, v92
	v_mul_f32_e32 v93, 0xbfb8aa3b, v93
	v_mul_f32_e32 v94, 0xbfb8aa3b, v94
	v_mul_f32_e32 v95, 0xbfb8aa3b, v95
	v_exp_f32_e32 v92, v92
	v_exp_f32_e32 v93, v93
	v_exp_f32_e32 v94, v94
	v_exp_f32_e32 v95, v95
	v_add_f32_e32 v92, 1.0, v92
	v_add_f32_e32 v93, 1.0, v93
	v_add_f32_e32 v94, 1.0, v94
	v_add_f32_e32 v95, 1.0, v95
	v_rcp_f32_e32 v220, v92
	v_rcp_f32_e32 v221, v93
	v_rcp_f32_e32 v222, v94
	v_rcp_f32_e32 v223, v95
	v_fma_f32 v224, -v92, v220, 1.0
	v_fma_f32 v225, -v93, v221, 1.0
	v_fma_f32 v226, -v94, v222, 1.0
	v_fma_f32 v227, -v95, v223, 1.0
	v_fma_f32 v92, v224, v220, v220
	v_fma_f32 v93, v225, v221, v221
	v_fma_f32 v94, v226, v222, v222
	v_fma_f32 v95, v227, v223, v223
	v_lshlrev_b32_e32 v230, 16, v182
	v_and_b32_e32 v182, 0xffff0000, v182
	v_lshlrev_b32_e32 v231, 16, v183
	v_and_b32_e32 v183, 0xffff0000, v183
	v_lshlrev_b32_e32 v232, 16, v184
	v_and_b32_e32 v184, 0xffff0000, v184
	v_lshlrev_b32_e32 v233, 16, v185
	v_and_b32_e32 v185, 0xffff0000, v185
	v_fma_f32 v92, v92, v232, v230
	v_fma_f32 v93, v93, v184, v182
	v_fma_f32 v94, v94, v233, v231
	v_fma_f32 v95, v95, v185, v183
	v_mul_f32_e32 v228, v92, v92
	v_fmac_f32_e32 v228, v93, v93
	v_fmac_f32_e32 v228, v94, v94
	v_fmac_f32_e32 v228, v95, v95
	v_cvt_pk_bf16_f32 v182, v92, v93
	v_cvt_pk_bf16_f32 v183, v94, v95
	global_store_dwordx2 v188, v[182:183], s[62:63] offset:0
	v_mul_f32_e32 v88, v88, v210
	v_mul_f32_e32 v89, v89, v210
	v_mul_f32_e32 v90, v90, v210
	v_mul_f32_e32 v91, v91, v210
	v_mul_f32_e32 v88, 0xbfb8aa3b, v88
	v_mul_f32_e32 v89, 0xbfb8aa3b, v89
	v_mul_f32_e32 v90, 0xbfb8aa3b, v90
	v_mul_f32_e32 v91, 0xbfb8aa3b, v91
	v_exp_f32_e32 v88, v88
	v_exp_f32_e32 v89, v89
	v_exp_f32_e32 v90, v90
	v_exp_f32_e32 v91, v91
	v_add_f32_e32 v88, 1.0, v88
	v_add_f32_e32 v89, 1.0, v89
	v_add_f32_e32 v90, 1.0, v90
	v_add_f32_e32 v91, 1.0, v91
	v_rcp_f32_e32 v220, v88
	v_rcp_f32_e32 v221, v89
	v_rcp_f32_e32 v222, v90
	v_rcp_f32_e32 v223, v91
	v_fma_f32 v224, -v88, v220, 1.0
	v_fma_f32 v225, -v89, v221, 1.0
	v_fma_f32 v226, -v90, v222, 1.0
	v_fma_f32 v227, -v91, v223, 1.0
	v_fma_f32 v88, v224, v220, v220
	v_fma_f32 v89, v225, v221, v221
	v_fma_f32 v90, v226, v222, v222
	v_fma_f32 v91, v227, v223, v223
	v_lshlrev_b32_e32 v230, 16, v186
	v_and_b32_e32 v186, 0xffff0000, v186
	v_lshlrev_b32_e32 v231, 16, v187
	v_and_b32_e32 v187, 0xffff0000, v187
	v_lshlrev_b32_e32 v232, 16, v200
	v_and_b32_e32 v200, 0xffff0000, v200
	v_lshlrev_b32_e32 v233, 16, v201
	v_and_b32_e32 v201, 0xffff0000, v201
	v_fma_f32 v88, v88, v232, v230
	v_fma_f32 v89, v89, v200, v186
	v_fma_f32 v90, v90, v233, v231
	v_fma_f32 v91, v91, v201, v187
	v_fmac_f32_e32 v228, v88, v88
	v_fmac_f32_e32 v228, v89, v89
	v_fmac_f32_e32 v228, v90, v90
	v_fmac_f32_e32 v228, v91, v91
	v_cvt_pk_bf16_f32 v186, v88, v89
	v_cvt_pk_bf16_f32 v187, v90, v91
	global_store_dwordx2 v188, v[186:187], s[62:63] offset:32
	v_mul_f32_e32 v84, v84, v210
	v_mul_f32_e32 v85, v85, v210
	v_mul_f32_e32 v86, v86, v210
	v_mul_f32_e32 v87, v87, v210
	v_mul_f32_e32 v84, 0xbfb8aa3b, v84
	v_mul_f32_e32 v85, 0xbfb8aa3b, v85
	v_mul_f32_e32 v86, 0xbfb8aa3b, v86
	v_mul_f32_e32 v87, 0xbfb8aa3b, v87
	v_exp_f32_e32 v84, v84
	v_exp_f32_e32 v85, v85
	v_exp_f32_e32 v86, v86
	v_exp_f32_e32 v87, v87
	v_add_f32_e32 v84, 1.0, v84
	v_add_f32_e32 v85, 1.0, v85
	v_add_f32_e32 v86, 1.0, v86
	v_add_f32_e32 v87, 1.0, v87
	v_rcp_f32_e32 v220, v84
	v_rcp_f32_e32 v221, v85
	v_rcp_f32_e32 v222, v86
	v_rcp_f32_e32 v223, v87
	v_fma_f32 v224, -v84, v220, 1.0
	v_fma_f32 v225, -v85, v221, 1.0
	v_fma_f32 v226, -v86, v222, 1.0
	v_fma_f32 v227, -v87, v223, 1.0
	v_fma_f32 v84, v224, v220, v220
	v_fma_f32 v85, v225, v221, v221
	v_fma_f32 v86, v226, v222, v222
	v_fma_f32 v87, v227, v223, v223
	v_lshlrev_b32_e32 v230, 16, v202
	v_and_b32_e32 v202, 0xffff0000, v202
	v_lshlrev_b32_e32 v231, 16, v203
	v_and_b32_e32 v203, 0xffff0000, v203
	v_lshlrev_b32_e32 v232, 16, v204
	v_and_b32_e32 v204, 0xffff0000, v204
	v_lshlrev_b32_e32 v233, 16, v205
	v_and_b32_e32 v205, 0xffff0000, v205
	v_fma_f32 v84, v84, v232, v230
	v_fma_f32 v85, v85, v204, v202
	v_fma_f32 v86, v86, v233, v231
	v_fma_f32 v87, v87, v205, v203
	v_fmac_f32_e32 v228, v84, v84
	v_fmac_f32_e32 v228, v85, v85
	v_fmac_f32_e32 v228, v86, v86
	v_fmac_f32_e32 v228, v87, v87
	v_cvt_pk_bf16_f32 v202, v84, v85
	v_cvt_pk_bf16_f32 v203, v86, v87
	global_store_dwordx2 v188, v[202:203], s[62:63] offset:256
	v_mul_f32_e32 v80, v80, v210
	v_mul_f32_e32 v81, v81, v210
	v_mul_f32_e32 v82, v82, v210
	v_mul_f32_e32 v83, v83, v210
	v_mul_f32_e32 v80, 0xbfb8aa3b, v80
	v_mul_f32_e32 v81, 0xbfb8aa3b, v81
	v_mul_f32_e32 v82, 0xbfb8aa3b, v82
	v_mul_f32_e32 v83, 0xbfb8aa3b, v83
	v_exp_f32_e32 v80, v80
	v_exp_f32_e32 v81, v81
	v_exp_f32_e32 v82, v82
	v_exp_f32_e32 v83, v83
	v_add_f32_e32 v80, 1.0, v80
	v_add_f32_e32 v81, 1.0, v81
	v_add_f32_e32 v82, 1.0, v82
	v_add_f32_e32 v83, 1.0, v83
	v_rcp_f32_e32 v220, v80
	v_rcp_f32_e32 v221, v81
	v_rcp_f32_e32 v222, v82
	v_rcp_f32_e32 v223, v83
	v_fma_f32 v224, -v80, v220, 1.0
	v_fma_f32 v225, -v81, v221, 1.0
	v_fma_f32 v226, -v82, v222, 1.0
	v_fma_f32 v227, -v83, v223, 1.0
	v_fma_f32 v80, v224, v220, v220
	v_fma_f32 v81, v225, v221, v221
	v_fma_f32 v82, v226, v222, v222
	v_fma_f32 v83, v227, v223, v223
	v_lshlrev_b32_e32 v230, 16, v134
	v_and_b32_e32 v134, 0xffff0000, v134
	v_lshlrev_b32_e32 v231, 16, v135
	v_and_b32_e32 v135, 0xffff0000, v135
	v_lshlrev_b32_e32 v232, 16, v136
	v_and_b32_e32 v136, 0xffff0000, v136
	v_lshlrev_b32_e32 v233, 16, v137
	v_and_b32_e32 v137, 0xffff0000, v137
	v_fma_f32 v80, v80, v232, v230
	v_fma_f32 v81, v81, v136, v134
	v_fma_f32 v82, v82, v233, v231
	v_fma_f32 v83, v83, v137, v135
	v_fmac_f32_e32 v228, v80, v80
	v_fmac_f32_e32 v228, v81, v81
	v_fmac_f32_e32 v228, v82, v82
	v_fmac_f32_e32 v228, v83, v83
	v_cvt_pk_bf16_f32 v134, v80, v81
	v_cvt_pk_bf16_f32 v135, v82, v83
	global_store_dwordx2 v188, v[134:135], s[62:63] offset:288
	ds_bpermute_b32 v229, v207, v228
	s_waitcnt lgkmcnt(0)
	v_add_f32_e32 v228, v228, v229
	ds_bpermute_b32 v229, v206, v228
	s_waitcnt lgkmcnt(0)
	v_add_f32_e32 v228, v228, v229
	v_add_u32_e32 v252, 0x1000, v198
	v_cmp_gt_u32_e32 vcc, 16, v147
	s_and_saveexec_b64 s[2:3], vcc
	global_store_dword v252, v228, s[98:99]
	s_or_b64 exec, exec, s[2:3]
	v_add_u32_e32 v192, 0x30000, v140
	v_mul_f32_e32 v76, v76, v211
	v_mul_f32_e32 v77, v77, v211
	v_mul_f32_e32 v78, v78, v211
	v_mul_f32_e32 v79, v79, v211
	v_mul_f32_e32 v76, 0xbfb8aa3b, v76
	v_mul_f32_e32 v77, 0xbfb8aa3b, v77
	v_mul_f32_e32 v78, 0xbfb8aa3b, v78
	v_mul_f32_e32 v79, 0xbfb8aa3b, v79
	v_exp_f32_e32 v76, v76
	v_exp_f32_e32 v77, v77
	v_exp_f32_e32 v78, v78
	v_exp_f32_e32 v79, v79
	v_add_f32_e32 v76, 1.0, v76
	v_add_f32_e32 v77, 1.0, v77
	v_add_f32_e32 v78, 1.0, v78
	v_add_f32_e32 v79, 1.0, v79
	v_rcp_f32_e32 v220, v76
	v_rcp_f32_e32 v221, v77
	v_rcp_f32_e32 v222, v78
	v_rcp_f32_e32 v223, v79
	v_fma_f32 v224, -v76, v220, 1.0
	v_fma_f32 v225, -v77, v221, 1.0
	v_fma_f32 v226, -v78, v222, 1.0
	v_fma_f32 v227, -v79, v223, 1.0
	v_fma_f32 v76, v224, v220, v220
	v_fma_f32 v77, v225, v221, v221
	v_fma_f32 v78, v226, v222, v222
	v_fma_f32 v79, v227, v223, v223
	v_lshlrev_b32_e32 v230, 16, v138
	v_and_b32_e32 v138, 0xffff0000, v138
	v_lshlrev_b32_e32 v231, 16, v139
	v_and_b32_e32 v139, 0xffff0000, v139
	v_lshlrev_b32_e32 v232, 16, v142
	v_and_b32_e32 v142, 0xffff0000, v142
	v_lshlrev_b32_e32 v233, 16, v143
	v_and_b32_e32 v143, 0xffff0000, v143
	v_fma_f32 v76, v76, v232, v230
	v_fma_f32 v77, v77, v142, v138
	v_fma_f32 v78, v78, v233, v231
	v_fma_f32 v79, v79, v143, v139
	v_mul_f32_e32 v228, v76, v76
	v_fmac_f32_e32 v228, v77, v77
	v_fmac_f32_e32 v228, v78, v78
	v_fmac_f32_e32 v228, v79, v79
	v_cvt_pk_bf16_f32 v138, v76, v77
	v_cvt_pk_bf16_f32 v139, v78, v79
	global_store_dwordx2 v192, v[138:139], s[62:63] offset:0
	v_mul_f32_e32 v72, v72, v211
	v_mul_f32_e32 v73, v73, v211
	v_mul_f32_e32 v74, v74, v211
	v_mul_f32_e32 v75, v75, v211
	v_mul_f32_e32 v72, 0xbfb8aa3b, v72
	v_mul_f32_e32 v73, 0xbfb8aa3b, v73
	v_mul_f32_e32 v74, 0xbfb8aa3b, v74
	v_mul_f32_e32 v75, 0xbfb8aa3b, v75
	v_exp_f32_e32 v72, v72
	v_exp_f32_e32 v73, v73
	v_exp_f32_e32 v74, v74
	v_exp_f32_e32 v75, v75
	v_add_f32_e32 v72, 1.0, v72
	v_add_f32_e32 v73, 1.0, v73
	v_add_f32_e32 v74, 1.0, v74
	v_add_f32_e32 v75, 1.0, v75
	v_rcp_f32_e32 v220, v72
	v_rcp_f32_e32 v221, v73
	v_rcp_f32_e32 v222, v74
	v_rcp_f32_e32 v223, v75
	v_fma_f32 v224, -v72, v220, 1.0
	v_fma_f32 v225, -v73, v221, 1.0
	v_fma_f32 v226, -v74, v222, 1.0
	v_fma_f32 v227, -v75, v223, 1.0
	v_fma_f32 v72, v224, v220, v220
	v_fma_f32 v73, v225, v221, v221
	v_fma_f32 v74, v226, v222, v222
	v_fma_f32 v75, v227, v223, v223
	v_lshlrev_b32_e32 v230, 16, v144
	v_and_b32_e32 v144, 0xffff0000, v144
	v_lshlrev_b32_e32 v231, 16, v145
	v_and_b32_e32 v145, 0xffff0000, v145
	v_lshlrev_b32_e32 v232, 16, v190
	v_and_b32_e32 v190, 0xffff0000, v190
	v_lshlrev_b32_e32 v233, 16, v191
	v_and_b32_e32 v191, 0xffff0000, v191
	v_fma_f32 v72, v72, v232, v230
	v_fma_f32 v73, v73, v190, v144
	v_fma_f32 v74, v74, v233, v231
	v_fma_f32 v75, v75, v191, v145
	v_fmac_f32_e32 v228, v72, v72
	v_fmac_f32_e32 v228, v73, v73
	v_fmac_f32_e32 v228, v74, v74
	v_fmac_f32_e32 v228, v75, v75
	v_cvt_pk_bf16_f32 v144, v72, v73
	v_cvt_pk_bf16_f32 v145, v74, v75
	global_store_dwordx2 v192, v[144:145], s[62:63] offset:32
	v_mul_f32_e32 v68, v68, v211
	v_mul_f32_e32 v69, v69, v211
	v_mul_f32_e32 v70, v70, v211
	v_mul_f32_e32 v71, v71, v211
	v_mul_f32_e32 v68, 0xbfb8aa3b, v68
	v_mul_f32_e32 v69, 0xbfb8aa3b, v69
	v_mul_f32_e32 v70, 0xbfb8aa3b, v70
	v_mul_f32_e32 v71, 0xbfb8aa3b, v71
	v_exp_f32_e32 v68, v68
	v_exp_f32_e32 v69, v69
	v_exp_f32_e32 v70, v70
	v_exp_f32_e32 v71, v71
	v_add_f32_e32 v68, 1.0, v68
	v_add_f32_e32 v69, 1.0, v69
	v_add_f32_e32 v70, 1.0, v70
	v_add_f32_e32 v71, 1.0, v71
	v_rcp_f32_e32 v220, v68
	v_rcp_f32_e32 v221, v69
	v_rcp_f32_e32 v222, v70
	v_rcp_f32_e32 v223, v71
	v_fma_f32 v224, -v68, v220, 1.0
	v_fma_f32 v225, -v69, v221, 1.0
	v_fma_f32 v226, -v70, v222, 1.0
	v_fma_f32 v227, -v71, v223, 1.0
	v_fma_f32 v68, v224, v220, v220
	v_fma_f32 v69, v225, v221, v221
	v_fma_f32 v70, v226, v222, v222
	v_fma_f32 v71, v227, v223, v223
	v_lshlrev_b32_e32 v230, 16, v194
	v_and_b32_e32 v194, 0xffff0000, v194
	v_lshlrev_b32_e32 v231, 16, v195
	v_and_b32_e32 v195, 0xffff0000, v195
	v_lshlrev_b32_e32 v232, 16, v248
	v_and_b32_e32 v248, 0xffff0000, v248
	v_lshlrev_b32_e32 v233, 16, v249
	v_and_b32_e32 v249, 0xffff0000, v249
	v_fma_f32 v68, v68, v232, v230
	v_fma_f32 v69, v69, v248, v194
	v_fma_f32 v70, v70, v233, v231
	v_fma_f32 v71, v71, v249, v195
	v_fmac_f32_e32 v228, v68, v68
	v_fmac_f32_e32 v228, v69, v69
	v_fmac_f32_e32 v228, v70, v70
	v_fmac_f32_e32 v228, v71, v71
	v_cvt_pk_bf16_f32 v194, v68, v69
	v_cvt_pk_bf16_f32 v195, v70, v71
	global_store_dwordx2 v192, v[194:195], s[62:63] offset:256
	v_mul_f32_e32 v64, v64, v211
	v_mul_f32_e32 v65, v65, v211
	v_mul_f32_e32 v66, v66, v211
	v_mul_f32_e32 v67, v67, v211
	v_mul_f32_e32 v64, 0xbfb8aa3b, v64
	v_mul_f32_e32 v65, 0xbfb8aa3b, v65
	v_mul_f32_e32 v66, 0xbfb8aa3b, v66
	v_mul_f32_e32 v67, 0xbfb8aa3b, v67
	v_exp_f32_e32 v64, v64
	v_exp_f32_e32 v65, v65
	v_exp_f32_e32 v66, v66
	v_exp_f32_e32 v67, v67
	v_add_f32_e32 v64, 1.0, v64
	v_add_f32_e32 v65, 1.0, v65
	v_add_f32_e32 v66, 1.0, v66
	v_add_f32_e32 v67, 1.0, v67
	v_rcp_f32_e32 v220, v64
	v_rcp_f32_e32 v221, v65
	v_rcp_f32_e32 v222, v66
	v_rcp_f32_e32 v223, v67
	v_fma_f32 v224, -v64, v220, 1.0
	v_fma_f32 v225, -v65, v221, 1.0
	v_fma_f32 v226, -v66, v222, 1.0
	v_fma_f32 v227, -v67, v223, 1.0
	v_fma_f32 v64, v224, v220, v220
	v_fma_f32 v65, v225, v221, v221
	v_fma_f32 v66, v226, v222, v222
	v_fma_f32 v67, v227, v223, v223
	v_lshlrev_b32_e32 v230, 16, v150
	v_and_b32_e32 v150, 0xffff0000, v150
	v_lshlrev_b32_e32 v231, 16, v151
	v_and_b32_e32 v151, 0xffff0000, v151
	v_lshlrev_b32_e32 v232, 16, v238
	v_and_b32_e32 v238, 0xffff0000, v238
	v_lshlrev_b32_e32 v233, 16, v239
	v_and_b32_e32 v239, 0xffff0000, v239
	v_fma_f32 v64, v64, v232, v230
	v_fma_f32 v65, v65, v238, v150
	v_fma_f32 v66, v66, v233, v231
	v_fma_f32 v67, v67, v239, v151
	v_fmac_f32_e32 v228, v64, v64
	v_fmac_f32_e32 v228, v65, v65
	v_fmac_f32_e32 v228, v66, v66
	v_fmac_f32_e32 v228, v67, v67
	v_cvt_pk_bf16_f32 v150, v64, v65
	v_cvt_pk_bf16_f32 v151, v66, v67
	global_store_dwordx2 v192, v[150:151], s[62:63] offset:288
	ds_bpermute_b32 v229, v207, v228
	s_waitcnt lgkmcnt(0)
	v_add_f32_e32 v228, v228, v229
	ds_bpermute_b32 v229, v206, v228
	s_waitcnt lgkmcnt(0)
	v_add_f32_e32 v228, v228, v229
	v_add_u32_e32 v252, 0x1800, v198
	v_cmp_gt_u32_e32 vcc, 16, v147
	s_and_saveexec_b64 s[2:3], vcc
	global_store_dword v252, v228, s[98:99]
	s_or_b64 exec, exec, s[2:3]
	v_add_u32_e32 v196, 0xa0000, v140
	global_load_dwordx2 v[182:183], v196, s[58:59] offset:0
	global_load_dwordx2 v[184:185], v196, s[56:57] offset:0
	global_load_dwordx2 v[186:187], v196, s[58:59] offset:32
	global_load_dwordx2 v[200:201], v196, s[56:57] offset:32
	global_load_dwordx2 v[202:203], v196, s[58:59] offset:256
	global_load_dwordx2 v[204:205], v196, s[56:57] offset:256
	global_load_dwordx2 v[134:135], v196, s[58:59] offset:288
	global_load_dwordx2 v[136:137], v196, s[56:57] offset:288
	v_add_u32_e32 v148, 0xb0000, v140
	global_load_dwordx2 v[138:139], v148, s[58:59] offset:0
	global_load_dwordx2 v[142:143], v148, s[56:57] offset:0
	global_load_dwordx2 v[144:145], v148, s[58:59] offset:32
	global_load_dwordx2 v[190:191], v148, s[56:57] offset:32
	global_load_dwordx2 v[194:195], v148, s[58:59] offset:256
	global_load_dwordx2 v[248:249], v148, s[56:57] offset:256
	global_load_dwordx2 v[150:151], v148, s[58:59] offset:288
	v_add_u32_e32 v188, 0xb0000, v140
	global_load_dwordx2 v[234:235], v188, s[56:57] offset:288
	s_waitcnt vmcnt(42)
	v_add_f32_e32 v96, v96, v97
	v_add_f32_e32 v98, v98, v99
	v_add_f32_e32 v100, v100, v101
	v_add_f32_e32 v102, v102, v103
	v_add_f32_e32 v96, v96, v98
	v_add_f32_e32 v100, v100, v102
	v_add_f32_e32 v96, v96, v100
	v_add_f32_e32 v104, v104, v105
	v_add_f32_e32 v106, v106, v107
	v_add_f32_e32 v108, v108, v109
	v_add_f32_e32 v110, v110, v111
	v_add_f32_e32 v104, v104, v106
	v_add_f32_e32 v108, v108, v110
	v_add_f32_e32 v104, v104, v108
	v_add_f32_e32 v112, v112, v113
	v_add_f32_e32 v114, v114, v115
	v_add_f32_e32 v116, v116, v117
	v_add_f32_e32 v118, v118, v119
	v_add_f32_e32 v112, v112, v114
	v_add_f32_e32 v116, v116, v118
	v_add_f32_e32 v112, v112, v116
	v_add_f32_e32 v120, v120, v121
	v_add_f32_e32 v122, v122, v123
	v_add_f32_e32 v124, v124, v125
	v_add_f32_e32 v126, v126, v127
	v_add_f32_e32 v120, v120, v122
	v_add_f32_e32 v124, v124, v126
	v_add_f32_e32 v120, v120, v124
	ds_bpermute_b32 v97, v207, v96
	ds_bpermute_b32 v105, v207, v104
	ds_bpermute_b32 v113, v207, v112
	ds_bpermute_b32 v121, v207, v120
	s_waitcnt lgkmcnt(0)
	v_add_f32_e32 v96, v96, v97
	v_add_f32_e32 v104, v104, v105
	v_add_f32_e32 v112, v112, v113
	v_add_f32_e32 v120, v120, v121
	ds_bpermute_b32 v97, v206, v96
	ds_bpermute_b32 v105, v206, v104
	ds_bpermute_b32 v113, v206, v112
	ds_bpermute_b32 v121, v206, v120
	s_waitcnt lgkmcnt(0)
	v_add_f32_e32 v96, v96, v97
	v_add_f32_e32 v104, v104, v105
	v_add_f32_e32 v112, v112, v113
	v_add_f32_e32 v120, v120, v121
	v_mul_f32_e32 v96, 0x3a000000, v96
	v_add_f32_e32 v96, 0x358637bd, v96
	v_mul_f32_e32 v104, 0x3a000000, v104
	v_add_f32_e32 v104, 0x358637bd, v104
	v_mul_f32_e32 v112, 0x3a000000, v112
	v_add_f32_e32 v112, 0x358637bd, v112
	v_mul_f32_e32 v120, 0x3a000000, v120
	v_add_f32_e32 v120, 0x358637bd, v120
	v_rsq_f32_e32 v96, v96
	v_rsq_f32_e32 v104, v104
	v_rsq_f32_e32 v112, v112
	v_rsq_f32_e32 v120, v120
	s_nop 0
	v_mov_b32_e32 v212, v96
	v_mov_b32_e32 v213, v104
	v_mov_b32_e32 v214, v112
	v_mov_b32_e32 v215, v120
	s_waitcnt vmcnt(26)
	v_add_u32_e32 v192, 0x80000, v140
	v_mul_f32_e32 v60, v60, v212
	v_mul_f32_e32 v61, v61, v212
	v_mul_f32_e32 v62, v62, v212
	v_mul_f32_e32 v63, v63, v212
	v_mul_f32_e32 v60, 0xbfb8aa3b, v60
	v_mul_f32_e32 v61, 0xbfb8aa3b, v61
	v_mul_f32_e32 v62, 0xbfb8aa3b, v62
	v_mul_f32_e32 v63, 0xbfb8aa3b, v63
	v_exp_f32_e32 v60, v60
	v_exp_f32_e32 v61, v61
	v_exp_f32_e32 v62, v62
	v_exp_f32_e32 v63, v63
	v_add_f32_e32 v60, 1.0, v60
	v_add_f32_e32 v61, 1.0, v61
	v_add_f32_e32 v62, 1.0, v62
	v_add_f32_e32 v63, 1.0, v63
	v_rcp_f32_e32 v220, v60
	v_rcp_f32_e32 v221, v61
	v_rcp_f32_e32 v222, v62
	v_rcp_f32_e32 v223, v63
	v_fma_f32 v224, -v60, v220, 1.0
	v_fma_f32 v225, -v61, v221, 1.0
	v_fma_f32 v226, -v62, v222, 1.0
	v_fma_f32 v227, -v63, v223, 1.0
	v_fma_f32 v60, v224, v220, v220
	v_fma_f32 v61, v225, v221, v221
	v_fma_f32 v62, v226, v222, v222
	v_fma_f32 v63, v227, v223, v223
	v_lshlrev_b32_e32 v230, 16, v152
	v_and_b32_e32 v152, 0xffff0000, v152
	v_lshlrev_b32_e32 v231, 16, v153
	v_and_b32_e32 v153, 0xffff0000, v153
	v_lshlrev_b32_e32 v232, 16, v154
	v_and_b32_e32 v154, 0xffff0000, v154
	v_lshlrev_b32_e32 v233, 16, v155
	v_and_b32_e32 v155, 0xffff0000, v155
	v_fma_f32 v60, v60, v232, v230
	v_fma_f32 v61, v61, v154, v152
	v_fma_f32 v62, v62, v233, v231
	v_fma_f32 v63, v63, v155, v153
	v_mul_f32_e32 v228, v60, v60
	v_fmac_f32_e32 v228, v61, v61
	v_fmac_f32_e32 v228, v62, v62
	v_fmac_f32_e32 v228, v63, v63
	v_cvt_pk_bf16_f32 v152, v60, v61
	v_cvt_pk_bf16_f32 v153, v62, v63
	global_store_dwordx2 v192, v[152:153], s[62:63] offset:0
	v_mul_f32_e32 v56, v56, v212
	v_mul_f32_e32 v57, v57, v212
	v_mul_f32_e32 v58, v58, v212
	v_mul_f32_e32 v59, v59, v212
	v_mul_f32_e32 v56, 0xbfb8aa3b, v56
	v_mul_f32_e32 v57, 0xbfb8aa3b, v57
	v_mul_f32_e32 v58, 0xbfb8aa3b, v58
	v_mul_f32_e32 v59, 0xbfb8aa3b, v59
	v_exp_f32_e32 v56, v56
	v_exp_f32_e32 v57, v57
	v_exp_f32_e32 v58, v58
	v_exp_f32_e32 v59, v59
	v_add_f32_e32 v56, 1.0, v56
	v_add_f32_e32 v57, 1.0, v57
	v_add_f32_e32 v58, 1.0, v58
	v_add_f32_e32 v59, 1.0, v59
	v_rcp_f32_e32 v220, v56
	v_rcp_f32_e32 v221, v57
	v_rcp_f32_e32 v222, v58
	v_rcp_f32_e32 v223, v59
	v_fma_f32 v224, -v56, v220, 1.0
	v_fma_f32 v225, -v57, v221, 1.0
	v_fma_f32 v226, -v58, v222, 1.0
	v_fma_f32 v227, -v59, v223, 1.0
	v_fma_f32 v56, v224, v220, v220
	v_fma_f32 v57, v225, v221, v221
	v_fma_f32 v58, v226, v222, v222
	v_fma_f32 v59, v227, v223, v223
	v_lshlrev_b32_e32 v230, 16, v156
	v_and_b32_e32 v156, 0xffff0000, v156
	v_lshlrev_b32_e32 v231, 16, v157
	v_and_b32_e32 v157, 0xffff0000, v157
	v_lshlrev_b32_e32 v232, 16, v158
	v_and_b32_e32 v158, 0xffff0000, v158
	v_lshlrev_b32_e32 v233, 16, v159
	v_and_b32_e32 v159, 0xffff0000, v159
	v_fma_f32 v56, v56, v232, v230
	v_fma_f32 v57, v57, v158, v156
	v_fma_f32 v58, v58, v233, v231
	v_fma_f32 v59, v59, v159, v157
	v_fmac_f32_e32 v228, v56, v56
	v_fmac_f32_e32 v228, v57, v57
	v_fmac_f32_e32 v228, v58, v58
	v_fmac_f32_e32 v228, v59, v59
	v_cvt_pk_bf16_f32 v156, v56, v57
	v_cvt_pk_bf16_f32 v157, v58, v59
	global_store_dwordx2 v192, v[156:157], s[62:63] offset:32
	v_mul_f32_e32 v52, v52, v212
	v_mul_f32_e32 v53, v53, v212
	v_mul_f32_e32 v54, v54, v212
	v_mul_f32_e32 v55, v55, v212
	v_mul_f32_e32 v52, 0xbfb8aa3b, v52
	v_mul_f32_e32 v53, 0xbfb8aa3b, v53
	v_mul_f32_e32 v54, 0xbfb8aa3b, v54
	v_mul_f32_e32 v55, 0xbfb8aa3b, v55
	v_exp_f32_e32 v52, v52
	v_exp_f32_e32 v53, v53
	v_exp_f32_e32 v54, v54
	v_exp_f32_e32 v55, v55
	v_add_f32_e32 v52, 1.0, v52
	v_add_f32_e32 v53, 1.0, v53
	v_add_f32_e32 v54, 1.0, v54
	v_add_f32_e32 v55, 1.0, v55
	v_rcp_f32_e32 v220, v52
	v_rcp_f32_e32 v221, v53
	v_rcp_f32_e32 v222, v54
	v_rcp_f32_e32 v223, v55
	v_fma_f32 v224, -v52, v220, 1.0
	v_fma_f32 v225, -v53, v221, 1.0
	v_fma_f32 v226, -v54, v222, 1.0
	v_fma_f32 v227, -v55, v223, 1.0
	v_fma_f32 v52, v224, v220, v220
	v_fma_f32 v53, v225, v221, v221
	v_fma_f32 v54, v226, v222, v222
	v_fma_f32 v55, v227, v223, v223
	v_lshlrev_b32_e32 v230, 16, v160
	v_and_b32_e32 v160, 0xffff0000, v160
	v_lshlrev_b32_e32 v231, 16, v161
	v_and_b32_e32 v161, 0xffff0000, v161
	v_lshlrev_b32_e32 v232, 16, v162
	v_and_b32_e32 v162, 0xffff0000, v162
	v_lshlrev_b32_e32 v233, 16, v163
	v_and_b32_e32 v163, 0xffff0000, v163
	v_fma_f32 v52, v52, v232, v230
	v_fma_f32 v53, v53, v162, v160
	v_fma_f32 v54, v54, v233, v231
	v_fma_f32 v55, v55, v163, v161
	v_fmac_f32_e32 v228, v52, v52
	v_fmac_f32_e32 v228, v53, v53
	v_fmac_f32_e32 v228, v54, v54
	v_fmac_f32_e32 v228, v55, v55
	v_cvt_pk_bf16_f32 v160, v52, v53
	v_cvt_pk_bf16_f32 v161, v54, v55
	global_store_dwordx2 v192, v[160:161], s[62:63] offset:256
	v_mul_f32_e32 v48, v48, v212
	v_mul_f32_e32 v49, v49, v212
	v_mul_f32_e32 v50, v50, v212
	v_mul_f32_e32 v51, v51, v212
	v_mul_f32_e32 v48, 0xbfb8aa3b, v48
	v_mul_f32_e32 v49, 0xbfb8aa3b, v49
	v_mul_f32_e32 v50, 0xbfb8aa3b, v50
	v_mul_f32_e32 v51, 0xbfb8aa3b, v51
	v_exp_f32_e32 v48, v48
	v_exp_f32_e32 v49, v49
	v_exp_f32_e32 v50, v50
	v_exp_f32_e32 v51, v51
	v_add_f32_e32 v48, 1.0, v48
	v_add_f32_e32 v49, 1.0, v49
	v_add_f32_e32 v50, 1.0, v50
	v_add_f32_e32 v51, 1.0, v51
	v_rcp_f32_e32 v220, v48
	v_rcp_f32_e32 v221, v49
	v_rcp_f32_e32 v222, v50
	v_rcp_f32_e32 v223, v51
	v_fma_f32 v224, -v48, v220, 1.0
	v_fma_f32 v225, -v49, v221, 1.0
	v_fma_f32 v226, -v50, v222, 1.0
	v_fma_f32 v227, -v51, v223, 1.0
	v_fma_f32 v48, v224, v220, v220
	v_fma_f32 v49, v225, v221, v221
	v_fma_f32 v50, v226, v222, v222
	v_fma_f32 v51, v227, v223, v223
	v_lshlrev_b32_e32 v230, 16, v164
	v_and_b32_e32 v164, 0xffff0000, v164
	v_lshlrev_b32_e32 v231, 16, v165
	v_and_b32_e32 v165, 0xffff0000, v165
	v_lshlrev_b32_e32 v232, 16, v166
	v_and_b32_e32 v166, 0xffff0000, v166
	v_lshlrev_b32_e32 v233, 16, v167
	v_and_b32_e32 v167, 0xffff0000, v167
	v_fma_f32 v48, v48, v232, v230
	v_fma_f32 v49, v49, v166, v164
	v_fma_f32 v50, v50, v233, v231
	v_fma_f32 v51, v51, v167, v165
	v_fmac_f32_e32 v228, v48, v48
	v_fmac_f32_e32 v228, v49, v49
	v_fmac_f32_e32 v228, v50, v50
	v_fmac_f32_e32 v228, v51, v51
	v_cvt_pk_bf16_f32 v164, v48, v49
	v_cvt_pk_bf16_f32 v165, v50, v51
	global_store_dwordx2 v192, v[164:165], s[62:63] offset:288
	ds_bpermute_b32 v229, v207, v228
	s_waitcnt lgkmcnt(0)
	v_add_f32_e32 v228, v228, v229
	ds_bpermute_b32 v229, v206, v228
	s_waitcnt lgkmcnt(0)
	v_add_f32_e32 v228, v228, v229
	v_add_u32_e32 v252, 0x4000, v198
	v_cmp_gt_u32_e32 vcc, 16, v147
	s_and_saveexec_b64 s[2:3], vcc
	global_store_dword v252, v228, s[98:99]
	s_or_b64 exec, exec, s[2:3]
	v_add_u32_e32 v196, 0x90000, v140
	v_mul_f32_e32 v44, v44, v213
	v_mul_f32_e32 v45, v45, v213
	v_mul_f32_e32 v46, v46, v213
	v_mul_f32_e32 v47, v47, v213
	v_mul_f32_e32 v44, 0xbfb8aa3b, v44
	v_mul_f32_e32 v45, 0xbfb8aa3b, v45
	v_mul_f32_e32 v46, 0xbfb8aa3b, v46
	v_mul_f32_e32 v47, 0xbfb8aa3b, v47
	v_exp_f32_e32 v44, v44
	v_exp_f32_e32 v45, v45
	v_exp_f32_e32 v46, v46
	v_exp_f32_e32 v47, v47
	v_add_f32_e32 v44, 1.0, v44
	v_add_f32_e32 v45, 1.0, v45
	v_add_f32_e32 v46, 1.0, v46
	v_add_f32_e32 v47, 1.0, v47
	v_rcp_f32_e32 v220, v44
	v_rcp_f32_e32 v221, v45
	v_rcp_f32_e32 v222, v46
	v_rcp_f32_e32 v223, v47
	v_fma_f32 v224, -v44, v220, 1.0
	v_fma_f32 v225, -v45, v221, 1.0
	v_fma_f32 v226, -v46, v222, 1.0
	v_fma_f32 v227, -v47, v223, 1.0
	v_fma_f32 v44, v224, v220, v220
	v_fma_f32 v45, v225, v221, v221
	v_fma_f32 v46, v226, v222, v222
	v_fma_f32 v47, v227, v223, v223
	v_lshlrev_b32_e32 v230, 16, v168
	v_and_b32_e32 v168, 0xffff0000, v168
	v_lshlrev_b32_e32 v231, 16, v169
	v_and_b32_e32 v169, 0xffff0000, v169
	v_lshlrev_b32_e32 v232, 16, v170
	v_and_b32_e32 v170, 0xffff0000, v170
	v_lshlrev_b32_e32 v233, 16, v171
	v_and_b32_e32 v171, 0xffff0000, v171
	v_fma_f32 v44, v44, v232, v230
	v_fma_f32 v45, v45, v170, v168
	v_fma_f32 v46, v46, v233, v231
	v_fma_f32 v47, v47, v171, v169
	v_mul_f32_e32 v228, v44, v44
	v_fmac_f32_e32 v228, v45, v45
	v_fmac_f32_e32 v228, v46, v46
	v_fmac_f32_e32 v228, v47, v47
	v_cvt_pk_bf16_f32 v168, v44, v45
	v_cvt_pk_bf16_f32 v169, v46, v47
	global_store_dwordx2 v196, v[168:169], s[62:63] offset:0
	v_mul_f32_e32 v40, v40, v213
	v_mul_f32_e32 v41, v41, v213
	v_mul_f32_e32 v42, v42, v213
	v_mul_f32_e32 v43, v43, v213
	v_mul_f32_e32 v40, 0xbfb8aa3b, v40
	v_mul_f32_e32 v41, 0xbfb8aa3b, v41
	v_mul_f32_e32 v42, 0xbfb8aa3b, v42
	v_mul_f32_e32 v43, 0xbfb8aa3b, v43
	v_exp_f32_e32 v40, v40
	v_exp_f32_e32 v41, v41
	v_exp_f32_e32 v42, v42
	v_exp_f32_e32 v43, v43
	v_add_f32_e32 v40, 1.0, v40
	v_add_f32_e32 v41, 1.0, v41
	v_add_f32_e32 v42, 1.0, v42
	v_add_f32_e32 v43, 1.0, v43
	v_rcp_f32_e32 v220, v40
	v_rcp_f32_e32 v221, v41
	v_rcp_f32_e32 v222, v42
	v_rcp_f32_e32 v223, v43
	v_fma_f32 v224, -v40, v220, 1.0
	v_fma_f32 v225, -v41, v221, 1.0
	v_fma_f32 v226, -v42, v222, 1.0
	v_fma_f32 v227, -v43, v223, 1.0
	v_fma_f32 v40, v224, v220, v220
	v_fma_f32 v41, v225, v221, v221
	v_fma_f32 v42, v226, v222, v222
	v_fma_f32 v43, v227, v223, v223
	v_lshlrev_b32_e32 v230, 16, v172
	v_and_b32_e32 v172, 0xffff0000, v172
	v_lshlrev_b32_e32 v231, 16, v173
	v_and_b32_e32 v173, 0xffff0000, v173
	v_lshlrev_b32_e32 v232, 16, v174
	v_and_b32_e32 v174, 0xffff0000, v174
	v_lshlrev_b32_e32 v233, 16, v175
	v_and_b32_e32 v175, 0xffff0000, v175
	v_fma_f32 v40, v40, v232, v230
	v_fma_f32 v41, v41, v174, v172
	v_fma_f32 v42, v42, v233, v231
	v_fma_f32 v43, v43, v175, v173
	v_fmac_f32_e32 v228, v40, v40
	v_fmac_f32_e32 v228, v41, v41
	v_fmac_f32_e32 v228, v42, v42
	v_fmac_f32_e32 v228, v43, v43
	v_cvt_pk_bf16_f32 v172, v40, v41
	v_cvt_pk_bf16_f32 v173, v42, v43
	global_store_dwordx2 v196, v[172:173], s[62:63] offset:32
	v_mul_f32_e32 v36, v36, v213
	v_mul_f32_e32 v37, v37, v213
	v_mul_f32_e32 v38, v38, v213
	v_mul_f32_e32 v39, v39, v213
	v_mul_f32_e32 v36, 0xbfb8aa3b, v36
	v_mul_f32_e32 v37, 0xbfb8aa3b, v37
	v_mul_f32_e32 v38, 0xbfb8aa3b, v38
	v_mul_f32_e32 v39, 0xbfb8aa3b, v39
	v_exp_f32_e32 v36, v36
	v_exp_f32_e32 v37, v37
	v_exp_f32_e32 v38, v38
	v_exp_f32_e32 v39, v39
	v_add_f32_e32 v36, 1.0, v36
	v_add_f32_e32 v37, 1.0, v37
	v_add_f32_e32 v38, 1.0, v38
	v_add_f32_e32 v39, 1.0, v39
	v_rcp_f32_e32 v220, v36
	v_rcp_f32_e32 v221, v37
	v_rcp_f32_e32 v222, v38
	v_rcp_f32_e32 v223, v39
	v_fma_f32 v224, -v36, v220, 1.0
	v_fma_f32 v225, -v37, v221, 1.0
	v_fma_f32 v226, -v38, v222, 1.0
	v_fma_f32 v227, -v39, v223, 1.0
	v_fma_f32 v36, v224, v220, v220
	v_fma_f32 v37, v225, v221, v221
	v_fma_f32 v38, v226, v222, v222
	v_fma_f32 v39, v227, v223, v223
	v_lshlrev_b32_e32 v230, 16, v240
	v_and_b32_e32 v240, 0xffff0000, v240
	v_lshlrev_b32_e32 v231, 16, v241
	v_and_b32_e32 v241, 0xffff0000, v241
	v_lshlrev_b32_e32 v232, 16, v242
	v_and_b32_e32 v242, 0xffff0000, v242
	v_lshlrev_b32_e32 v233, 16, v243
	v_and_b32_e32 v243, 0xffff0000, v243
	v_fma_f32 v36, v36, v232, v230
	v_fma_f32 v37, v37, v242, v240
	v_fma_f32 v38, v38, v233, v231
	v_fma_f32 v39, v39, v243, v241
	v_fmac_f32_e32 v228, v36, v36
	v_fmac_f32_e32 v228, v37, v37
	v_fmac_f32_e32 v228, v38, v38
	v_fmac_f32_e32 v228, v39, v39
	v_cvt_pk_bf16_f32 v240, v36, v37
	v_cvt_pk_bf16_f32 v241, v38, v39
	global_store_dwordx2 v196, v[240:241], s[62:63] offset:256
	v_mul_f32_e32 v32, v32, v213
	v_mul_f32_e32 v33, v33, v213
	v_mul_f32_e32 v34, v34, v213
	v_mul_f32_e32 v35, v35, v213
	v_mul_f32_e32 v32, 0xbfb8aa3b, v32
	v_mul_f32_e32 v33, 0xbfb8aa3b, v33
	v_mul_f32_e32 v34, 0xbfb8aa3b, v34
	v_mul_f32_e32 v35, 0xbfb8aa3b, v35
	v_exp_f32_e32 v32, v32
	v_exp_f32_e32 v33, v33
	v_exp_f32_e32 v34, v34
	v_exp_f32_e32 v35, v35
	v_add_f32_e32 v32, 1.0, v32
	v_add_f32_e32 v33, 1.0, v33
	v_add_f32_e32 v34, 1.0, v34
	v_add_f32_e32 v35, 1.0, v35
	v_rcp_f32_e32 v220, v32
	v_rcp_f32_e32 v221, v33
	v_rcp_f32_e32 v222, v34
	v_rcp_f32_e32 v223, v35
	v_fma_f32 v224, -v32, v220, 1.0
	v_fma_f32 v225, -v33, v221, 1.0
	v_fma_f32 v226, -v34, v222, 1.0
	v_fma_f32 v227, -v35, v223, 1.0
	v_fma_f32 v32, v224, v220, v220
	v_fma_f32 v33, v225, v221, v221
	v_fma_f32 v34, v226, v222, v222
	v_fma_f32 v35, v227, v223, v223
	v_lshlrev_b32_e32 v230, 16, v244
	v_and_b32_e32 v244, 0xffff0000, v244
	v_lshlrev_b32_e32 v231, 16, v245
	v_and_b32_e32 v245, 0xffff0000, v245
	v_lshlrev_b32_e32 v232, 16, v246
	v_and_b32_e32 v246, 0xffff0000, v246
	v_lshlrev_b32_e32 v233, 16, v247
	v_and_b32_e32 v247, 0xffff0000, v247
	v_fma_f32 v32, v32, v232, v230
	v_fma_f32 v33, v33, v246, v244
	v_fma_f32 v34, v34, v233, v231
	v_fma_f32 v35, v35, v247, v245
	v_fmac_f32_e32 v228, v32, v32
	v_fmac_f32_e32 v228, v33, v33
	v_fmac_f32_e32 v228, v34, v34
	v_fmac_f32_e32 v228, v35, v35
	v_cvt_pk_bf16_f32 v244, v32, v33
	v_cvt_pk_bf16_f32 v245, v34, v35
	global_store_dwordx2 v196, v[244:245], s[62:63] offset:288
	ds_bpermute_b32 v229, v207, v228
	s_waitcnt lgkmcnt(0)
	v_add_f32_e32 v228, v228, v229
	ds_bpermute_b32 v229, v206, v228
	s_waitcnt lgkmcnt(0)
	v_add_f32_e32 v228, v228, v229
	v_add_u32_e32 v252, 0x4800, v198
	v_cmp_gt_u32_e32 vcc, 16, v147
	s_and_saveexec_b64 s[2:3], vcc
	global_store_dword v252, v228, s[98:99]
	s_or_b64 exec, exec, s[2:3]
	s_waitcnt vmcnt(10)
	v_add_u32_e32 v148, 0xa0000, v140
	v_mul_f32_e32 v28, v28, v214
	v_mul_f32_e32 v29, v29, v214
	v_mul_f32_e32 v30, v30, v214
	v_mul_f32_e32 v31, v31, v214
	v_mul_f32_e32 v28, 0xbfb8aa3b, v28
	v_mul_f32_e32 v29, 0xbfb8aa3b, v29
	v_mul_f32_e32 v30, 0xbfb8aa3b, v30
	v_mul_f32_e32 v31, 0xbfb8aa3b, v31
	v_exp_f32_e32 v28, v28
	v_exp_f32_e32 v29, v29
	v_exp_f32_e32 v30, v30
	v_exp_f32_e32 v31, v31
	v_add_f32_e32 v28, 1.0, v28
	v_add_f32_e32 v29, 1.0, v29
	v_add_f32_e32 v30, 1.0, v30
	v_add_f32_e32 v31, 1.0, v31
	v_rcp_f32_e32 v220, v28
	v_rcp_f32_e32 v221, v29
	v_rcp_f32_e32 v222, v30
	v_rcp_f32_e32 v223, v31
	v_fma_f32 v224, -v28, v220, 1.0
	v_fma_f32 v225, -v29, v221, 1.0
	v_fma_f32 v226, -v30, v222, 1.0
	v_fma_f32 v227, -v31, v223, 1.0
	v_fma_f32 v28, v224, v220, v220
	v_fma_f32 v29, v225, v221, v221
	v_fma_f32 v30, v226, v222, v222
	v_fma_f32 v31, v227, v223, v223
	v_lshlrev_b32_e32 v230, 16, v182
	v_and_b32_e32 v182, 0xffff0000, v182
	v_lshlrev_b32_e32 v231, 16, v183
	v_and_b32_e32 v183, 0xffff0000, v183
	v_lshlrev_b32_e32 v232, 16, v184
	v_and_b32_e32 v184, 0xffff0000, v184
	v_lshlrev_b32_e32 v233, 16, v185
	v_and_b32_e32 v185, 0xffff0000, v185
	v_fma_f32 v28, v28, v232, v230
	v_fma_f32 v29, v29, v184, v182
	v_fma_f32 v30, v30, v233, v231
	v_fma_f32 v31, v31, v185, v183
	v_mul_f32_e32 v228, v28, v28
	v_fmac_f32_e32 v228, v29, v29
	v_fmac_f32_e32 v228, v30, v30
	v_fmac_f32_e32 v228, v31, v31
	v_cvt_pk_bf16_f32 v182, v28, v29
	v_cvt_pk_bf16_f32 v183, v30, v31
	global_store_dwordx2 v148, v[182:183], s[62:63] offset:0
	v_mul_f32_e32 v24, v24, v214
	v_mul_f32_e32 v25, v25, v214
	v_mul_f32_e32 v26, v26, v214
	v_mul_f32_e32 v27, v27, v214
	v_mul_f32_e32 v24, 0xbfb8aa3b, v24
	v_mul_f32_e32 v25, 0xbfb8aa3b, v25
	v_mul_f32_e32 v26, 0xbfb8aa3b, v26
	v_mul_f32_e32 v27, 0xbfb8aa3b, v27
	v_exp_f32_e32 v24, v24
	v_exp_f32_e32 v25, v25
	v_exp_f32_e32 v26, v26
	v_exp_f32_e32 v27, v27
	v_add_f32_e32 v24, 1.0, v24
	v_add_f32_e32 v25, 1.0, v25
	v_add_f32_e32 v26, 1.0, v26
	v_add_f32_e32 v27, 1.0, v27
	v_rcp_f32_e32 v220, v24
	v_rcp_f32_e32 v221, v25
	v_rcp_f32_e32 v222, v26
	v_rcp_f32_e32 v223, v27
	v_fma_f32 v224, -v24, v220, 1.0
	v_fma_f32 v225, -v25, v221, 1.0
	v_fma_f32 v226, -v26, v222, 1.0
	v_fma_f32 v227, -v27, v223, 1.0
	v_fma_f32 v24, v224, v220, v220
	v_fma_f32 v25, v225, v221, v221
	v_fma_f32 v26, v226, v222, v222
	v_fma_f32 v27, v227, v223, v223
	v_lshlrev_b32_e32 v230, 16, v186
	v_and_b32_e32 v186, 0xffff0000, v186
	v_lshlrev_b32_e32 v231, 16, v187
	v_and_b32_e32 v187, 0xffff0000, v187
	v_lshlrev_b32_e32 v232, 16, v200
	v_and_b32_e32 v200, 0xffff0000, v200
	v_lshlrev_b32_e32 v233, 16, v201
	v_and_b32_e32 v201, 0xffff0000, v201
	v_fma_f32 v24, v24, v232, v230
	v_fma_f32 v25, v25, v200, v186
	v_fma_f32 v26, v26, v233, v231
	v_fma_f32 v27, v27, v201, v187
	v_fmac_f32_e32 v228, v24, v24
	v_fmac_f32_e32 v228, v25, v25
	v_fmac_f32_e32 v228, v26, v26
	v_fmac_f32_e32 v228, v27, v27
	v_cvt_pk_bf16_f32 v186, v24, v25
	v_cvt_pk_bf16_f32 v187, v26, v27
	global_store_dwordx2 v148, v[186:187], s[62:63] offset:32
	v_mul_f32_e32 v20, v20, v214
	v_mul_f32_e32 v21, v21, v214
	v_mul_f32_e32 v22, v22, v214
	v_mul_f32_e32 v23, v23, v214
	v_mul_f32_e32 v20, 0xbfb8aa3b, v20
	v_mul_f32_e32 v21, 0xbfb8aa3b, v21
	v_mul_f32_e32 v22, 0xbfb8aa3b, v22
	v_mul_f32_e32 v23, 0xbfb8aa3b, v23
	v_exp_f32_e32 v20, v20
	v_exp_f32_e32 v21, v21
	v_exp_f32_e32 v22, v22
	v_exp_f32_e32 v23, v23
	v_add_f32_e32 v20, 1.0, v20
	v_add_f32_e32 v21, 1.0, v21
	v_add_f32_e32 v22, 1.0, v22
	v_add_f32_e32 v23, 1.0, v23
	v_rcp_f32_e32 v220, v20
	v_rcp_f32_e32 v221, v21
	v_rcp_f32_e32 v222, v22
	v_rcp_f32_e32 v223, v23
	v_fma_f32 v224, -v20, v220, 1.0
	v_fma_f32 v225, -v21, v221, 1.0
	v_fma_f32 v226, -v22, v222, 1.0
	v_fma_f32 v227, -v23, v223, 1.0
	v_fma_f32 v20, v224, v220, v220
	v_fma_f32 v21, v225, v221, v221
	v_fma_f32 v22, v226, v222, v222
	v_fma_f32 v23, v227, v223, v223
	v_lshlrev_b32_e32 v230, 16, v202
	v_and_b32_e32 v202, 0xffff0000, v202
	v_lshlrev_b32_e32 v231, 16, v203
	v_and_b32_e32 v203, 0xffff0000, v203
	v_lshlrev_b32_e32 v232, 16, v204
	v_and_b32_e32 v204, 0xffff0000, v204
	v_lshlrev_b32_e32 v233, 16, v205
	v_and_b32_e32 v205, 0xffff0000, v205
	v_fma_f32 v20, v20, v232, v230
	v_fma_f32 v21, v21, v204, v202
	v_fma_f32 v22, v22, v233, v231
	v_fma_f32 v23, v23, v205, v203
	v_fmac_f32_e32 v228, v20, v20
	v_fmac_f32_e32 v228, v21, v21
	v_fmac_f32_e32 v228, v22, v22
	v_fmac_f32_e32 v228, v23, v23
	v_cvt_pk_bf16_f32 v202, v20, v21
	v_cvt_pk_bf16_f32 v203, v22, v23
	global_store_dwordx2 v148, v[202:203], s[62:63] offset:256
	v_mul_f32_e32 v16, v16, v214
	v_mul_f32_e32 v17, v17, v214
	v_mul_f32_e32 v18, v18, v214
	v_mul_f32_e32 v19, v19, v214
	v_mul_f32_e32 v16, 0xbfb8aa3b, v16
	v_mul_f32_e32 v17, 0xbfb8aa3b, v17
	v_mul_f32_e32 v18, 0xbfb8aa3b, v18
	v_mul_f32_e32 v19, 0xbfb8aa3b, v19
	v_exp_f32_e32 v16, v16
	v_exp_f32_e32 v17, v17
	v_exp_f32_e32 v18, v18
	v_exp_f32_e32 v19, v19
	v_add_f32_e32 v16, 1.0, v16
	v_add_f32_e32 v17, 1.0, v17
	v_add_f32_e32 v18, 1.0, v18
	v_add_f32_e32 v19, 1.0, v19
	v_rcp_f32_e32 v220, v16
	v_rcp_f32_e32 v221, v17
	v_rcp_f32_e32 v222, v18
	v_rcp_f32_e32 v223, v19
	v_fma_f32 v224, -v16, v220, 1.0
	v_fma_f32 v225, -v17, v221, 1.0
	v_fma_f32 v226, -v18, v222, 1.0
	v_fma_f32 v227, -v19, v223, 1.0
	v_fma_f32 v16, v224, v220, v220
	v_fma_f32 v17, v225, v221, v221
	v_fma_f32 v18, v226, v222, v222
	v_fma_f32 v19, v227, v223, v223
	v_lshlrev_b32_e32 v230, 16, v134
	v_and_b32_e32 v134, 0xffff0000, v134
	v_lshlrev_b32_e32 v231, 16, v135
	v_and_b32_e32 v135, 0xffff0000, v135
	v_lshlrev_b32_e32 v232, 16, v136
	v_and_b32_e32 v136, 0xffff0000, v136
	v_lshlrev_b32_e32 v233, 16, v137
	v_and_b32_e32 v137, 0xffff0000, v137
	v_fma_f32 v16, v16, v232, v230
	v_fma_f32 v17, v17, v136, v134
	v_fma_f32 v18, v18, v233, v231
	v_fma_f32 v19, v19, v137, v135
	v_fmac_f32_e32 v228, v16, v16
	v_fmac_f32_e32 v228, v17, v17
	v_fmac_f32_e32 v228, v18, v18
	v_fmac_f32_e32 v228, v19, v19
	v_cvt_pk_bf16_f32 v134, v16, v17
	v_cvt_pk_bf16_f32 v135, v18, v19
	global_store_dwordx2 v148, v[134:135], s[62:63] offset:288
	ds_bpermute_b32 v229, v207, v228
	s_waitcnt lgkmcnt(0)
	v_add_f32_e32 v228, v228, v229
	ds_bpermute_b32 v229, v206, v228
	s_waitcnt lgkmcnt(0)
	v_add_f32_e32 v228, v228, v229
	v_add_u32_e32 v252, 0x5000, v198
	v_cmp_gt_u32_e32 vcc, 16, v147
	s_and_saveexec_b64 s[2:3], vcc
	global_store_dword v252, v228, s[98:99]
	s_or_b64 exec, exec, s[2:3]
	v_add_u32_e32 v188, 0xb0000, v140
	v_mul_f32_e32 v12, v12, v215
	v_mul_f32_e32 v13, v13, v215
	v_mul_f32_e32 v14, v14, v215
	v_mul_f32_e32 v15, v15, v215
	v_mul_f32_e32 v12, 0xbfb8aa3b, v12
	v_mul_f32_e32 v13, 0xbfb8aa3b, v13
	v_mul_f32_e32 v14, 0xbfb8aa3b, v14
	v_mul_f32_e32 v15, 0xbfb8aa3b, v15
	v_exp_f32_e32 v12, v12
	v_exp_f32_e32 v13, v13
	v_exp_f32_e32 v14, v14
	v_exp_f32_e32 v15, v15
	v_add_f32_e32 v12, 1.0, v12
	v_add_f32_e32 v13, 1.0, v13
	v_add_f32_e32 v14, 1.0, v14
	v_add_f32_e32 v15, 1.0, v15
	v_rcp_f32_e32 v220, v12
	v_rcp_f32_e32 v221, v13
	v_rcp_f32_e32 v222, v14
	v_rcp_f32_e32 v223, v15
	v_fma_f32 v224, -v12, v220, 1.0
	v_fma_f32 v225, -v13, v221, 1.0
	v_fma_f32 v226, -v14, v222, 1.0
	v_fma_f32 v227, -v15, v223, 1.0
	v_fma_f32 v12, v224, v220, v220
	v_fma_f32 v13, v225, v221, v221
	v_fma_f32 v14, v226, v222, v222
	v_fma_f32 v15, v227, v223, v223
	v_lshlrev_b32_e32 v230, 16, v138
	v_and_b32_e32 v138, 0xffff0000, v138
	v_lshlrev_b32_e32 v231, 16, v139
	v_and_b32_e32 v139, 0xffff0000, v139
	v_lshlrev_b32_e32 v232, 16, v142
	v_and_b32_e32 v142, 0xffff0000, v142
	v_lshlrev_b32_e32 v233, 16, v143
	v_and_b32_e32 v143, 0xffff0000, v143
	v_fma_f32 v12, v12, v232, v230
	v_fma_f32 v13, v13, v142, v138
	v_fma_f32 v14, v14, v233, v231
	v_fma_f32 v15, v15, v143, v139
	v_mul_f32_e32 v228, v12, v12
	v_fmac_f32_e32 v228, v13, v13
	v_fmac_f32_e32 v228, v14, v14
	v_fmac_f32_e32 v228, v15, v15
	v_cvt_pk_bf16_f32 v138, v12, v13
	v_cvt_pk_bf16_f32 v139, v14, v15
	global_store_dwordx2 v188, v[138:139], s[62:63] offset:0
	v_mul_f32_e32 v8, v8, v215
	v_mul_f32_e32 v9, v9, v215
	v_mul_f32_e32 v10, v10, v215
	v_mul_f32_e32 v11, v11, v215
	v_mul_f32_e32 v8, 0xbfb8aa3b, v8
	v_mul_f32_e32 v9, 0xbfb8aa3b, v9
	v_mul_f32_e32 v10, 0xbfb8aa3b, v10
	v_mul_f32_e32 v11, 0xbfb8aa3b, v11
	v_exp_f32_e32 v8, v8
	v_exp_f32_e32 v9, v9
	v_exp_f32_e32 v10, v10
	v_exp_f32_e32 v11, v11
	v_add_f32_e32 v8, 1.0, v8
	v_add_f32_e32 v9, 1.0, v9
	v_add_f32_e32 v10, 1.0, v10
	v_add_f32_e32 v11, 1.0, v11
	v_rcp_f32_e32 v220, v8
	v_rcp_f32_e32 v221, v9
	v_rcp_f32_e32 v222, v10
	v_rcp_f32_e32 v223, v11
	v_fma_f32 v224, -v8, v220, 1.0
	v_fma_f32 v225, -v9, v221, 1.0
	v_fma_f32 v226, -v10, v222, 1.0
	v_fma_f32 v227, -v11, v223, 1.0
	v_fma_f32 v8, v224, v220, v220
	v_fma_f32 v9, v225, v221, v221
	v_fma_f32 v10, v226, v222, v222
	v_fma_f32 v11, v227, v223, v223
	v_lshlrev_b32_e32 v230, 16, v144
	v_and_b32_e32 v144, 0xffff0000, v144
	v_lshlrev_b32_e32 v231, 16, v145
	v_and_b32_e32 v145, 0xffff0000, v145
	v_lshlrev_b32_e32 v232, 16, v190
	v_and_b32_e32 v190, 0xffff0000, v190
	v_lshlrev_b32_e32 v233, 16, v191
	v_and_b32_e32 v191, 0xffff0000, v191
	v_fma_f32 v8, v8, v232, v230
	v_fma_f32 v9, v9, v190, v144
	v_fma_f32 v10, v10, v233, v231
	v_fma_f32 v11, v11, v191, v145
	v_fmac_f32_e32 v228, v8, v8
	v_fmac_f32_e32 v228, v9, v9
	v_fmac_f32_e32 v228, v10, v10
	v_fmac_f32_e32 v228, v11, v11
	v_cvt_pk_bf16_f32 v144, v8, v9
	v_cvt_pk_bf16_f32 v145, v10, v11
	global_store_dwordx2 v188, v[144:145], s[62:63] offset:32
	v_mul_f32_e32 v4, v4, v215
	v_mul_f32_e32 v5, v5, v215
	v_mul_f32_e32 v6, v6, v215
	v_mul_f32_e32 v7, v7, v215
	v_mul_f32_e32 v4, 0xbfb8aa3b, v4
	v_mul_f32_e32 v5, 0xbfb8aa3b, v5
	v_mul_f32_e32 v6, 0xbfb8aa3b, v6
	v_mul_f32_e32 v7, 0xbfb8aa3b, v7
	v_exp_f32_e32 v4, v4
	v_exp_f32_e32 v5, v5
	v_exp_f32_e32 v6, v6
	v_exp_f32_e32 v7, v7
	v_add_f32_e32 v4, 1.0, v4
	v_add_f32_e32 v5, 1.0, v5
	v_add_f32_e32 v6, 1.0, v6
	v_add_f32_e32 v7, 1.0, v7
	v_rcp_f32_e32 v220, v4
	v_rcp_f32_e32 v221, v5
	v_rcp_f32_e32 v222, v6
	v_rcp_f32_e32 v223, v7
	v_fma_f32 v224, -v4, v220, 1.0
	v_fma_f32 v225, -v5, v221, 1.0
	v_fma_f32 v226, -v6, v222, 1.0
	v_fma_f32 v227, -v7, v223, 1.0
	v_fma_f32 v4, v224, v220, v220
	v_fma_f32 v5, v225, v221, v221
	v_fma_f32 v6, v226, v222, v222
	v_fma_f32 v7, v227, v223, v223
	v_lshlrev_b32_e32 v230, 16, v194
	v_and_b32_e32 v194, 0xffff0000, v194
	v_lshlrev_b32_e32 v231, 16, v195
	v_and_b32_e32 v195, 0xffff0000, v195
	v_lshlrev_b32_e32 v232, 16, v248
	v_and_b32_e32 v248, 0xffff0000, v248
	v_lshlrev_b32_e32 v233, 16, v249
	v_and_b32_e32 v249, 0xffff0000, v249
	v_fma_f32 v4, v4, v232, v230
	v_fma_f32 v5, v5, v248, v194
	v_fma_f32 v6, v6, v233, v231
	v_fma_f32 v7, v7, v249, v195
	v_fmac_f32_e32 v228, v4, v4
	v_fmac_f32_e32 v228, v5, v5
	v_fmac_f32_e32 v228, v6, v6
	v_fmac_f32_e32 v228, v7, v7
	v_cvt_pk_bf16_f32 v194, v4, v5
	v_cvt_pk_bf16_f32 v195, v6, v7
	global_store_dwordx2 v188, v[194:195], s[62:63] offset:256
	v_mul_f32_e32 v0, v0, v215
	v_mul_f32_e32 v1, v1, v215
	v_mul_f32_e32 v2, v2, v215
	v_mul_f32_e32 v3, v3, v215
	v_mul_f32_e32 v0, 0xbfb8aa3b, v0
	v_mul_f32_e32 v1, 0xbfb8aa3b, v1
	v_mul_f32_e32 v2, 0xbfb8aa3b, v2
	v_mul_f32_e32 v3, 0xbfb8aa3b, v3
	v_exp_f32_e32 v0, v0
	v_exp_f32_e32 v1, v1
	v_exp_f32_e32 v2, v2
	v_exp_f32_e32 v3, v3
	v_add_f32_e32 v0, 1.0, v0
	v_add_f32_e32 v1, 1.0, v1
	v_add_f32_e32 v2, 1.0, v2
	v_add_f32_e32 v3, 1.0, v3
	v_rcp_f32_e32 v220, v0
	v_rcp_f32_e32 v221, v1
	v_rcp_f32_e32 v222, v2
	v_rcp_f32_e32 v223, v3
	v_fma_f32 v224, -v0, v220, 1.0
	v_fma_f32 v225, -v1, v221, 1.0
	v_fma_f32 v226, -v2, v222, 1.0
	v_fma_f32 v227, -v3, v223, 1.0
	v_fma_f32 v0, v224, v220, v220
	v_fma_f32 v1, v225, v221, v221
	v_fma_f32 v2, v226, v222, v222
	v_fma_f32 v3, v227, v223, v223
	v_lshlrev_b32_e32 v230, 16, v150
	v_and_b32_e32 v150, 0xffff0000, v150
	v_lshlrev_b32_e32 v231, 16, v151
	v_and_b32_e32 v151, 0xffff0000, v151
	v_lshlrev_b32_e32 v232, 16, v234
	v_and_b32_e32 v234, 0xffff0000, v234
	v_lshlrev_b32_e32 v233, 16, v235
	v_and_b32_e32 v235, 0xffff0000, v235
	v_fma_f32 v0, v0, v232, v230
	v_fma_f32 v1, v1, v234, v150
	v_fma_f32 v2, v2, v233, v231
	v_fma_f32 v3, v3, v235, v151
	v_fmac_f32_e32 v228, v0, v0
	v_fmac_f32_e32 v228, v1, v1
	v_fmac_f32_e32 v228, v2, v2
	v_fmac_f32_e32 v228, v3, v3
	v_cvt_pk_bf16_f32 v150, v0, v1
	v_cvt_pk_bf16_f32 v151, v2, v3
	global_store_dwordx2 v188, v[150:151], s[62:63] offset:288
	ds_bpermute_b32 v229, v207, v228
	s_waitcnt lgkmcnt(0)
	v_add_f32_e32 v228, v228, v229
	ds_bpermute_b32 v229, v206, v228
	s_waitcnt lgkmcnt(0)
	v_add_f32_e32 v228, v228, v229
	v_add_u32_e32 v252, 0x5800, v198
	v_cmp_gt_u32_e32 vcc, 16, v147
	s_and_saveexec_b64 s[2:3], vcc
	global_store_dword v252, v228, s[98:99]
	s_or_b64 exec, exec, s[2:3]
	s_and_b64 vcc, exec, s[40:41]
	s_cbranch_vccz .LBB0_640
	s_waitcnt vmcnt(0)
	s_cmpk_gt_u32 s89, 0xff
	s_cbranch_scc1 .LBB0_651
	s_barrier
